# GEMM K-loops: dropped the redundant lgkmcnt(0) wait right after the MFMA-opening barrier (already waited before it); stacked on stack20
# baseline (speedup 1.0000x reference)
; #define PG8_STAGE(bufoff, gbase, voff) do { _Pragma("unroll") for (int _i = 0; _i < 2; ++_i) \
;         __builtin_amdgcn_global_load_lds((const unsigned*)((const char*)(gbase) + (voff)[_i]), (PG8_LAS unsigned*)(lds + (bufoff) + ldsw + _i * 8192), 16, 0, 0); } while (0)
; #define PG8_LDA(dst, b, h) do { _Pragma("unroll") for (int m = 0; m < 4; ++m) _Pragma("unroll") for (int k = 0; k < 2; ++k) dst[m][k] = *(const PG8_LAS bf16x8*)(lds + PG8_SA(b, h) + aoff + m * 2048 + k * 1024); } while (0)
; #define PG8_LDB(dst, b, h) do { _Pragma("unroll") for (int n = 0; n < 2; ++n) _Pragma("unroll") for (int k = 0; k < 2; ++k) dst[n][k] = *(const PG8_LAS bf16x8*)(lds + PG8_SB(b, h) + boff + n * 2048 + k * 1024); } while (0)
; #define PG8_MMA(ai, bj, At, Bt) do { __builtin_amdgcn_s_setprio(1); _Pragma("unroll") for (int m = 0; m < 4; ++m) _Pragma("unroll") for (int n = 0; n < 2; ++n) _Pragma("unroll") for (int k = 0; k < 2; ++k) \
;         acc[ai][bj][m][n] = __builtin_amdgcn_mfma_f32_16x16x32_bf16(Bt[n][k], At[m][k], acc[ai][bj][m][n], 0, 0, 0); __builtin_amdgcn_s_setprio(0); } while (0)
; #define PG8_WAIT_V(n) asm volatile("s_waitcnt vmcnt(" #n ")" ::: "memory")
; #define PG8_WAIT_L(n) asm volatile("s_waitcnt lgkmcnt(" #n ")" ::: "memory")
; template <class Epi, class Sched, bool ALIGN_EPI = false, bool SP2 = false>
; __device__ __forceinline__ void gemm_phase(PG8_LAS unsigned char* lds, const Gemm g, const Sched& S, const Epi& E) {
;     ...
;             const bool last = (t == nt - 2);
;             const char* a1 = cA + (size_t)(t + 1) * kstep;
;             const char* a2 = last ? nA : cA + (size_t)(t + 2) * kstep; const char* b2 = last ? nB : cB + (size_t)(t + 2) * kstep;
;             const char* a3 = a2 + kstep; const char* b3 = b2 + kstep;
;             if (last && has_next) S.a_ready(nxt);
;             if constexpr (SP2) {
;             PG8_LDB(B0, 0, 0); PG8_LDB(B1, 0, 1); PG8_SCHED; PG8_LDA(At, 0, 0); PG8_STAGE(PG8_SA(1, 1), a1 + hstep, voffA);
;             PG8_WAIT_V(8); PG8_WAIT_L(0); PG8_BAR; PG8_MMA(0, 0, At, B0); PG8_MMA(0, 1, At, B1); PG8_BAR; PG8_SCHED;
;             PG8_LDA(At, 0, 1); PG8_STAGE(PG8_SB(0, 0), b2, voffB); PG8_STAGE(PG8_SB(0, 1), b2 + hstep, voffB); PG8_STAGE(PG8_SA(0, 0), a2, voffA);
;             PG8_WAIT_V(8); PG8_WAIT_L(0); PG8_BAR; PG8_MMA(1, 0, At, B0); PG8_MMA(1, 1, At, B1); PG8_BAR; PG8_SCHED;
.Lsp_1:
.LBB0_164:
	s_add_u32 s58, s72, 0xfffc0080
	s_addc_u32 s59, s73, -1
	s_add_i32 s84, 0, 0x10000
	s_cmp_eq_u32 s94, 12
	s_cselect_b32 s65, s36, s59
	s_cselect_b32 s64, s37, s58
	v_add_u32_e32 v140, s84, v146
	s_cselect_b32 s59, s51, s93
	s_cselect_b32 s58, s53, s92
	s_add_i32 s96, 0, 0x14000
	ds_read_b128 v[142:145], v140
	ds_read_b128 v[150:153], v140 offset:1024
	ds_read_b128 v[154:157], v140 offset:2048
	ds_read_b128 v[158:161], v140 offset:3072
	v_add_u32_e32 v140, s96, v146
	ds_read_b128 v[162:165], v140
	ds_read_b128 v[166:169], v140 offset:1024
	ds_read_b128 v[170:173], v140 offset:2048
	ds_read_b128 v[174:177], v140 offset:3072
	v_lshl_add_u64 v[186:187], s[72:73], 0, v[136:137]
	s_add_i32 m0, s19, 0xc000
	ds_read_b128 v[178:181], v148
	ds_read_b128 v[182:185], v148 offset:1024
	ds_read_b128 v[190:193], v148 offset:2048
	ds_read_b128 v[194:197], v148 offset:3072
	ds_read_b128 v[198:201], v148 offset:4096
	ds_read_b128 v[202:205], v148 offset:5120
	ds_read_b128 v[206:209], v148 offset:6144
	ds_read_b128 v[228:231], v148 offset:7168
	global_load_lds_dwordx4 v[186:187], off
	v_lshl_add_u64 v[186:187], s[72:73], 0, v[138:139]
	s_add_i32 m0, s19, 0xe000
	s_nop 0
	global_load_lds_dwordx4 v[186:187], off
	s_waitcnt vmcnt(8)
	s_waitcnt lgkmcnt(0)
	s_barrier
	v_mfma_f32_16x16x32_bf16 v[124:127], v[142:145], v[178:181], v[124:127]
	v_mfma_f32_16x16x32_bf16 v[120:123], v[154:157], v[178:181], v[120:123]
	v_mfma_f32_16x16x32_bf16 v[116:119], v[142:145], v[190:193], v[116:119]
	v_mfma_f32_16x16x32_bf16 v[112:115], v[154:157], v[190:193], v[112:115]
	v_mfma_f32_16x16x32_bf16 v[108:111], v[142:145], v[198:201], v[108:111]
	v_mfma_f32_16x16x32_bf16 v[104:107], v[154:157], v[198:201], v[104:107]
	v_mfma_f32_16x16x32_bf16 v[100:103], v[142:145], v[206:209], v[100:103]
	v_mfma_f32_16x16x32_bf16 v[96:99], v[154:157], v[206:209], v[96:99]
	v_mfma_f32_16x16x32_bf16 v[124:127], v[150:153], v[182:185], v[124:127]
	v_mfma_f32_16x16x32_bf16 v[120:123], v[158:161], v[182:185], v[120:123]
	v_mfma_f32_16x16x32_bf16 v[116:119], v[150:153], v[194:197], v[116:119]
	v_mfma_f32_16x16x32_bf16 v[112:115], v[158:161], v[194:197], v[112:115]
	v_mfma_f32_16x16x32_bf16 v[108:111], v[150:153], v[202:205], v[108:111]
	v_mfma_f32_16x16x32_bf16 v[104:107], v[158:161], v[202:205], v[104:107]
	v_mfma_f32_16x16x32_bf16 v[100:103], v[150:153], v[228:231], v[100:103]
	v_mfma_f32_16x16x32_bf16 v[96:99], v[158:161], v[228:231], v[96:99]
	v_mfma_f32_16x16x32_bf16 v[92:95], v[162:165], v[178:181], v[92:95]
	v_mfma_f32_16x16x32_bf16 v[88:91], v[170:173], v[178:181], v[88:91]
	v_mfma_f32_16x16x32_bf16 v[84:87], v[162:165], v[190:193], v[84:87]
	v_mfma_f32_16x16x32_bf16 v[80:83], v[170:173], v[190:193], v[80:83]
	v_mfma_f32_16x16x32_bf16 v[76:79], v[162:165], v[198:201], v[76:79]
	v_mfma_f32_16x16x32_bf16 v[72:75], v[170:173], v[198:201], v[72:75]
	v_mfma_f32_16x16x32_bf16 v[68:71], v[162:165], v[206:209], v[68:71]
	v_mfma_f32_16x16x32_bf16 v[64:67], v[170:173], v[206:209], v[64:67]
	v_mfma_f32_16x16x32_bf16 v[92:95], v[166:169], v[182:185], v[92:95]
	v_mfma_f32_16x16x32_bf16 v[88:91], v[174:177], v[182:185], v[88:91]
	v_mfma_f32_16x16x32_bf16 v[84:87], v[166:169], v[194:197], v[84:87]
	v_mfma_f32_16x16x32_bf16 v[80:83], v[174:177], v[194:197], v[80:83]
	v_mfma_f32_16x16x32_bf16 v[76:79], v[166:169], v[202:205], v[76:79]
	v_mfma_f32_16x16x32_bf16 v[72:75], v[174:177], v[202:205], v[72:75]
	v_mfma_f32_16x16x32_bf16 v[68:71], v[166:169], v[228:231], v[68:71]
	v_mfma_f32_16x16x32_bf16 v[64:67], v[174:177], v[228:231], v[64:67]
	s_barrier
	s_add_i32 s84, s84, s18
	v_lshl_add_u64 v[186:187], s[58:59], 0, v[128:129]
	s_mov_b32 m0, s84
	ds_read_b128 v[178:181], v148 offset:16384
	ds_read_b128 v[182:185], v148 offset:17408
	ds_read_b128 v[190:193], v148 offset:18432
	ds_read_b128 v[194:197], v148 offset:19456
	ds_read_b128 v[198:201], v148 offset:20480
	ds_read_b128 v[202:205], v148 offset:21504
	ds_read_b128 v[206:209], v148 offset:22528
	ds_read_b128 v[228:231], v148 offset:23552
	global_load_lds_dwordx4 v[186:187], off
	s_add_i32 m0, s84, 0x2000
	s_add_u32 s84, s58, 0x40000
	v_lshl_add_u64 v[188:189], s[58:59], 0, v[130:131]
	s_addc_u32 s85, s59, 0
	s_add_i32 s96, s96, s18
	global_load_lds_dwordx4 v[188:189], off
	v_lshl_add_u64 v[210:211], s[84:85], 0, v[128:129]
	s_mov_b32 m0, s96
	v_lshl_add_u64 v[232:233], s[64:65], 0, v[132:133]
	global_load_lds_dwordx4 v[210:211], off
	v_lshl_add_u64 v[210:211], s[84:85], 0, v[130:131]
	s_add_i32 m0, s96, 0x2000
	s_nop 0
	global_load_lds_dwordx4 v[210:211], off
	v_lshl_add_u64 v[210:211], s[64:65], 0, v[134:135]
	s_mov_b32 m0, s19
	s_nop 0
	global_load_lds_dwordx4 v[210:211], off
	s_mov_b32 m0, s20
	s_nop 0
	global_load_lds_dwordx4 v[232:233], off
	s_waitcnt vmcnt(8)
	s_waitcnt lgkmcnt(0)
	s_barrier
; #define PG8_STAGE(bufoff, gbase, voff) do { _Pragma("unroll") for (int _i = 0; _i < 2; ++_i) \
;         __builtin_amdgcn_global_load_lds((const unsigned*)((const char*)(gbase) + (voff)[_i]), (PG8_LAS unsigned*)(lds + (bufoff) + ldsw + _i * 8192), 16, 0, 0); } while (0)
; #define PG8_LDA(dst, b, h) do { _Pragma("unroll") for (int m = 0; m < 4; ++m) _Pragma("unroll") for (int k = 0; k < 2; ++k) dst[m][k] = *(const PG8_LAS bf16x8*)(lds + PG8_SA(b, h) + aoff + m * 2048 + k * 1024); } while (0)
; #define PG8_LDB(dst, b, h) do { _Pragma("unroll") for (int n = 0; n < 2; ++n) _Pragma("unroll") for (int k = 0; k < 2; ++k) dst[n][k] = *(const PG8_LAS bf16x8*)(lds + PG8_SB(b, h) + boff + n * 2048 + k * 1024); } while (0)
; #define PG8_MMA(ai, bj, At, Bt) do { __builtin_amdgcn_s_setprio(1); _Pragma("unroll") for (int m = 0; m < 4; ++m) _Pragma("unroll") for (int n = 0; n < 2; ++n) _Pragma("unroll") for (int k = 0; k < 2; ++k) \
;         acc[ai][bj][m][n] = __builtin_amdgcn_mfma_f32_16x16x32_bf16(Bt[n][k], At[m][k], acc[ai][bj][m][n], 0, 0, 0); __builtin_amdgcn_s_setprio(0); } while (0)
; #define PG8_WAIT_V(n) asm volatile("s_waitcnt vmcnt(" #n ")" ::: "memory")
; template <class Epi, class Sched, bool ALIGN_EPI = false, bool SP2 = false>
; __device__ __forceinline__ void gemm_phase(PG8_LAS unsigned char* lds, const Gemm g, const Sched& S, const Epi& E) {
;     ...
;             PG8_LDB(B0, 0, 0); PG8_LDB(B1, 0, 1); PG8_SCHED; PG8_LDA(At, 0, 0); PG8_STAGE(PG8_SA(1, 1), a1 + hstep, voffA);
;             PG8_WAIT_V(8); PG8_WAIT_L(0); PG8_BAR; PG8_MMA(0, 0, At, B0); PG8_MMA(0, 1, At, B1); PG8_BAR; PG8_SCHED;
;             PG8_LDA(At, 0, 1); PG8_STAGE(PG8_SB(0, 0), b2, voffB); PG8_STAGE(PG8_SB(0, 1), b2 + hstep, voffB); PG8_STAGE(PG8_SA(0, 0), a2, voffA);
;             PG8_WAIT_V(8); PG8_WAIT_L(0); PG8_BAR; PG8_MMA(1, 0, At, B0); PG8_MMA(1, 1, At, B1); PG8_BAR; PG8_SCHED;
;             PG8_LDB(B0, 1, 0); PG8_LDB(B1, 1, 1); PG8_SCHED; PG8_LDA(At, 1, 0); PG8_STAGE(PG8_SA(0, 1), a2 + hstep, voffA);
;             PG8_WAIT_V(8); PG8_WAIT_L(0); PG8_BAR; PG8_MMA(0, 0, At, B0); PG8_MMA(0, 1, At, B1); PG8_BAR; PG8_SCHED;
;             PG8_LDA(At, 1, 1); PG8_STAGE(PG8_SB(1, 0), b3, voffB); PG8_STAGE(PG8_SB(1, 1), b3 + hstep, voffB); PG8_STAGE(PG8_SA(1, 0), a3, voffA);
;             PG8_WAIT_V(8); PG8_WAIT_L(0); PG8_BAR; PG8_MMA(1, 0, At, B0); PG8_MMA(1, 1, At, B1); PG8_BAR; PG8_SCHED;
	v_mfma_f32_16x16x32_bf16 v[60:63], v[142:145], v[178:181], v[60:63]
	v_mfma_f32_16x16x32_bf16 v[56:59], v[154:157], v[178:181], v[56:59]
	v_mfma_f32_16x16x32_bf16 v[52:55], v[142:145], v[190:193], v[52:55]
	v_mfma_f32_16x16x32_bf16 v[48:51], v[154:157], v[190:193], v[48:51]
	v_mfma_f32_16x16x32_bf16 v[44:47], v[142:145], v[198:201], v[44:47]
	v_mfma_f32_16x16x32_bf16 v[40:43], v[154:157], v[198:201], v[40:43]
	v_mfma_f32_16x16x32_bf16 v[36:39], v[142:145], v[206:209], v[36:39]
	v_mfma_f32_16x16x32_bf16 v[32:35], v[154:157], v[206:209], v[32:35]
	v_mfma_f32_16x16x32_bf16 v[60:63], v[150:153], v[182:185], v[60:63]
	v_mfma_f32_16x16x32_bf16 v[56:59], v[158:161], v[182:185], v[56:59]
	v_mfma_f32_16x16x32_bf16 v[52:55], v[150:153], v[194:197], v[52:55]
	v_mfma_f32_16x16x32_bf16 v[48:51], v[158:161], v[194:197], v[48:51]
	v_mfma_f32_16x16x32_bf16 v[44:47], v[150:153], v[202:205], v[44:47]
	v_mfma_f32_16x16x32_bf16 v[40:43], v[158:161], v[202:205], v[40:43]
	v_mfma_f32_16x16x32_bf16 v[36:39], v[150:153], v[228:231], v[36:39]
	v_mfma_f32_16x16x32_bf16 v[32:35], v[158:161], v[228:231], v[32:35]
	v_mfma_f32_16x16x32_bf16 v[28:31], v[162:165], v[178:181], v[28:31]
	v_mfma_f32_16x16x32_bf16 v[24:27], v[170:173], v[178:181], v[24:27]
	v_mfma_f32_16x16x32_bf16 v[20:23], v[162:165], v[190:193], v[20:23]
	v_mfma_f32_16x16x32_bf16 v[16:19], v[170:173], v[190:193], v[16:19]
	v_mfma_f32_16x16x32_bf16 v[12:15], v[162:165], v[198:201], v[12:15]
	v_mfma_f32_16x16x32_bf16 v[8:11], v[170:173], v[198:201], v[8:11]
	v_mfma_f32_16x16x32_bf16 v[4:7], v[162:165], v[206:209], v[4:7]
	v_mfma_f32_16x16x32_bf16 v[0:3], v[170:173], v[206:209], v[0:3]
	v_mfma_f32_16x16x32_bf16 v[28:31], v[166:169], v[182:185], v[28:31]
	v_mfma_f32_16x16x32_bf16 v[24:27], v[174:177], v[182:185], v[24:27]
	v_mfma_f32_16x16x32_bf16 v[20:23], v[166:169], v[194:197], v[20:23]
	v_mfma_f32_16x16x32_bf16 v[16:19], v[174:177], v[194:197], v[16:19]
	v_mfma_f32_16x16x32_bf16 v[12:15], v[166:169], v[202:205], v[12:15]
	v_mfma_f32_16x16x32_bf16 v[8:11], v[174:177], v[202:205], v[8:11]
	v_mfma_f32_16x16x32_bf16 v[4:7], v[166:169], v[228:231], v[4:7]
	v_mfma_f32_16x16x32_bf16 v[0:3], v[174:177], v[228:231], v[0:3]
	s_barrier
	s_add_i32 s84, 0, 0x18000
	v_add_u32_e32 v140, s84, v146
	s_add_i32 s85, 0, 0x1c000
	ds_read_b128 v[142:145], v140
	ds_read_b128 v[150:153], v140 offset:1024
	ds_read_b128 v[154:157], v140 offset:2048
	ds_read_b128 v[158:161], v140 offset:3072
	v_add_u32_e32 v140, s85, v146
	ds_read_b128 v[162:165], v140
	ds_read_b128 v[166:169], v140 offset:1024
	ds_read_b128 v[170:173], v140 offset:2048
	ds_read_b128 v[174:177], v140 offset:3072
	s_add_u32 s64, s64, 0x40000
	s_addc_u32 s65, s65, 0
	s_mov_b32 m0, s21
	v_lshl_add_u64 v[234:235], s[64:65], 0, v[134:135]
	ds_read_b128 v[178:181], v148 offset:32768
	ds_read_b128 v[182:185], v148 offset:33792
	ds_read_b128 v[190:193], v148 offset:34816
	ds_read_b128 v[194:197], v148 offset:35840
	ds_read_b128 v[198:201], v148 offset:36864
	ds_read_b128 v[202:205], v148 offset:37888
	ds_read_b128 v[206:209], v148 offset:38912
	ds_read_b128 v[228:231], v148 offset:39936
	global_load_lds_dwordx4 v[234:235], off
	v_lshl_add_u64 v[234:235], s[64:65], 0, v[132:133]
	s_mov_b32 m0, s22
	s_nop 0
	global_load_lds_dwordx4 v[234:235], off
	s_waitcnt vmcnt(8)
	s_waitcnt lgkmcnt(0)
	s_barrier
	v_mfma_f32_16x16x32_bf16 v[124:127], v[142:145], v[178:181], v[124:127]
	v_mfma_f32_16x16x32_bf16 v[120:123], v[154:157], v[178:181], v[120:123]
	v_mfma_f32_16x16x32_bf16 v[116:119], v[142:145], v[190:193], v[116:119]
	v_mfma_f32_16x16x32_bf16 v[112:115], v[154:157], v[190:193], v[112:115]
	v_mfma_f32_16x16x32_bf16 v[108:111], v[142:145], v[198:201], v[108:111]
	v_mfma_f32_16x16x32_bf16 v[104:107], v[154:157], v[198:201], v[104:107]
	v_mfma_f32_16x16x32_bf16 v[100:103], v[142:145], v[206:209], v[100:103]
	v_mfma_f32_16x16x32_bf16 v[96:99], v[154:157], v[206:209], v[96:99]
	v_mfma_f32_16x16x32_bf16 v[124:127], v[150:153], v[182:185], v[124:127]
	v_mfma_f32_16x16x32_bf16 v[120:123], v[158:161], v[182:185], v[120:123]
	v_mfma_f32_16x16x32_bf16 v[116:119], v[150:153], v[194:197], v[116:119]
	v_mfma_f32_16x16x32_bf16 v[112:115], v[158:161], v[194:197], v[112:115]
	v_mfma_f32_16x16x32_bf16 v[108:111], v[150:153], v[202:205], v[108:111]
	v_mfma_f32_16x16x32_bf16 v[104:107], v[158:161], v[202:205], v[104:107]
	v_mfma_f32_16x16x32_bf16 v[100:103], v[150:153], v[228:231], v[100:103]
	v_mfma_f32_16x16x32_bf16 v[96:99], v[158:161], v[228:231], v[96:99]
	v_mfma_f32_16x16x32_bf16 v[92:95], v[162:165], v[178:181], v[92:95]
	v_mfma_f32_16x16x32_bf16 v[88:91], v[170:173], v[178:181], v[88:91]
	v_mfma_f32_16x16x32_bf16 v[84:87], v[162:165], v[190:193], v[84:87]
	v_mfma_f32_16x16x32_bf16 v[80:83], v[170:173], v[190:193], v[80:83]
	v_mfma_f32_16x16x32_bf16 v[76:79], v[162:165], v[198:201], v[76:79]
	v_mfma_f32_16x16x32_bf16 v[72:75], v[170:173], v[198:201], v[72:75]
	v_mfma_f32_16x16x32_bf16 v[68:71], v[162:165], v[206:209], v[68:71]
	v_mfma_f32_16x16x32_bf16 v[64:67], v[170:173], v[206:209], v[64:67]
	v_mfma_f32_16x16x32_bf16 v[92:95], v[166:169], v[182:185], v[92:95]
	v_mfma_f32_16x16x32_bf16 v[88:91], v[174:177], v[182:185], v[88:91]
	v_mfma_f32_16x16x32_bf16 v[84:87], v[166:169], v[194:197], v[84:87]
	v_mfma_f32_16x16x32_bf16 v[80:83], v[174:177], v[194:197], v[80:83]
	v_mfma_f32_16x16x32_bf16 v[76:79], v[166:169], v[202:205], v[76:79]
	v_mfma_f32_16x16x32_bf16 v[72:75], v[174:177], v[202:205], v[72:75]
	v_mfma_f32_16x16x32_bf16 v[68:71], v[166:169], v[228:231], v[68:71]
	v_mfma_f32_16x16x32_bf16 v[64:67], v[174:177], v[228:231], v[64:67]
	s_barrier
; #define PG8_STAGE(bufoff, gbase, voff) do { _Pragma("unroll") for (int _i = 0; _i < 2; ++_i) \
;         __builtin_amdgcn_global_load_lds((const unsigned*)((const char*)(gbase) + (voff)[_i]), (PG8_LAS unsigned*)(lds + (bufoff) + ldsw + _i * 8192), 16, 0, 0); } while (0)
; #define PG8_LDA(dst, b, h) do { _Pragma("unroll") for (int m = 0; m < 4; ++m) _Pragma("unroll") for (int k = 0; k < 2; ++k) dst[m][k] = *(const PG8_LAS bf16x8*)(lds + PG8_SA(b, h) + aoff + m * 2048 + k * 1024); } while (0)
; #define PG8_LDB(dst, b, h) do { _Pragma("unroll") for (int n = 0; n < 2; ++n) _Pragma("unroll") for (int k = 0; k < 2; ++k) dst[n][k] = *(const PG8_LAS bf16x8*)(lds + PG8_SB(b, h) + boff + n * 2048 + k * 1024); } while (0)
; #define PG8_MMA(ai, bj, At, Bt) do { __builtin_amdgcn_s_setprio(1); _Pragma("unroll") for (int m = 0; m < 4; ++m) _Pragma("unroll") for (int n = 0; n < 2; ++n) _Pragma("unroll") for (int k = 0; k < 2; ++k) \
;         acc[ai][bj][m][n] = __builtin_amdgcn_mfma_f32_16x16x32_bf16(Bt[n][k], At[m][k], acc[ai][bj][m][n], 0, 0, 0); __builtin_amdgcn_s_setprio(0); } while (0)
; template <class Epi, class Sched, bool ALIGN_EPI = false, bool SP2 = false>
; __device__ __forceinline__ void gemm_phase(PG8_LAS unsigned char* lds, const Gemm g, const Sched& S, const Epi& E) {
;     ...
;             PG8_LDB(B0, 0, 0); PG8_LDB(B1, 0, 1); PG8_SCHED; PG8_LDA(At, 0, 0); PG8_STAGE(PG8_SA(1, 1), a1 + hstep, voffA);
;             PG8_WAIT_V(8); PG8_WAIT_L(0); PG8_BAR; PG8_MMA(0, 0, At, B0); PG8_MMA(0, 1, At, B1); PG8_BAR; PG8_SCHED;
;             PG8_LDA(At, 0, 1); PG8_STAGE(PG8_SB(0, 0), b2, voffB); PG8_STAGE(PG8_SB(0, 1), b2 + hstep, voffB); PG8_STAGE(PG8_SA(0, 0), a2, voffA);
;             PG8_WAIT_V(8); PG8_WAIT_L(0); PG8_BAR; PG8_MMA(1, 0, At, B0); PG8_MMA(1, 1, At, B1); PG8_BAR; PG8_SCHED;
;             PG8_LDB(B0, 1, 0); PG8_LDB(B1, 1, 1); PG8_SCHED; PG8_LDA(At, 1, 0); PG8_STAGE(PG8_SA(0, 1), a2 + hstep, voffA);
;             PG8_WAIT_V(8); PG8_WAIT_L(0); PG8_BAR; PG8_MMA(0, 0, At, B0); PG8_MMA(0, 1, At, B1); PG8_BAR; PG8_SCHED;
;             PG8_LDA(At, 1, 1); PG8_STAGE(PG8_SB(1, 0), b3, voffB); PG8_STAGE(PG8_SB(1, 1), b3 + hstep, voffB); PG8_STAGE(PG8_SA(1, 0), a3, voffA);
;             PG8_WAIT_V(8); PG8_WAIT_L(0); PG8_BAR; PG8_MMA(1, 0, At, B0); PG8_MMA(1, 1, At, B1); PG8_BAR; PG8_SCHED;
;     ...
;         if constexpr (ALIGN_EPI) { if (wr == 0) PG8_BAR; }
	s_add_i32 s64, s84, s18
	v_lshl_add_u64 v[186:187], v[186:187], 0, s[90:91]
	s_mov_b32 m0, s64
	ds_read_b128 v[178:181], v148 offset:49152
	ds_read_b128 v[182:185], v148 offset:50176
	ds_read_b128 v[190:193], v148 offset:51200
	ds_read_b128 v[194:197], v148 offset:52224
	ds_read_b128 v[198:201], v148 offset:53248
	ds_read_b128 v[202:205], v148 offset:54272
	ds_read_b128 v[206:209], v148 offset:55296
	ds_read_b128 v[228:231], v148 offset:56320
	global_load_lds_dwordx4 v[186:187], off
	s_add_i32 m0, s64, 0x2000
	s_add_u32 s58, s58, 0x40080
	v_lshl_add_u64 v[186:187], v[188:189], 0, s[90:91]
	s_addc_u32 s59, s59, 0
	s_add_i32 s64, s85, s18
	global_load_lds_dwordx4 v[186:187], off
	v_lshl_add_u64 v[186:187], s[58:59], 0, v[128:129]
	s_mov_b32 m0, s64
	s_nop 0
	global_load_lds_dwordx4 v[186:187], off
	v_lshl_add_u64 v[186:187], s[58:59], 0, v[130:131]
	s_add_i32 m0, s64, 0x2000
	s_nop 0
	global_load_lds_dwordx4 v[186:187], off
	v_lshl_add_u64 v[186:187], v[210:211], 0, s[90:91]
	s_mov_b32 m0, s28
	s_nop 0
	global_load_lds_dwordx4 v[186:187], off
	v_lshl_add_u64 v[186:187], v[232:233], 0, s[90:91]
	s_mov_b32 m0, s29
	s_nop 0
	global_load_lds_dwordx4 v[186:187], off
	s_waitcnt vmcnt(8)
	s_waitcnt lgkmcnt(0)
	s_barrier
	v_mfma_f32_16x16x32_bf16 v[60:63], v[142:145], v[178:181], v[60:63]
	v_mfma_f32_16x16x32_bf16 v[56:59], v[154:157], v[178:181], v[56:59]
	v_mfma_f32_16x16x32_bf16 v[52:55], v[142:145], v[190:193], v[52:55]
	v_mfma_f32_16x16x32_bf16 v[48:51], v[154:157], v[190:193], v[48:51]
	v_mfma_f32_16x16x32_bf16 v[44:47], v[142:145], v[198:201], v[44:47]
	v_mfma_f32_16x16x32_bf16 v[40:43], v[154:157], v[198:201], v[40:43]
	v_mfma_f32_16x16x32_bf16 v[36:39], v[142:145], v[206:209], v[36:39]
	v_mfma_f32_16x16x32_bf16 v[32:35], v[154:157], v[206:209], v[32:35]
	v_mfma_f32_16x16x32_bf16 v[60:63], v[150:153], v[182:185], v[60:63]
	v_mfma_f32_16x16x32_bf16 v[56:59], v[158:161], v[182:185], v[56:59]
	v_mfma_f32_16x16x32_bf16 v[52:55], v[150:153], v[194:197], v[52:55]
	v_mfma_f32_16x16x32_bf16 v[48:51], v[158:161], v[194:197], v[48:51]
	v_mfma_f32_16x16x32_bf16 v[44:47], v[150:153], v[202:205], v[44:47]
	v_mfma_f32_16x16x32_bf16 v[40:43], v[158:161], v[202:205], v[40:43]
	v_mfma_f32_16x16x32_bf16 v[36:39], v[150:153], v[228:231], v[36:39]
	v_mfma_f32_16x16x32_bf16 v[32:35], v[158:161], v[228:231], v[32:35]
	v_mfma_f32_16x16x32_bf16 v[28:31], v[162:165], v[178:181], v[28:31]
	v_mfma_f32_16x16x32_bf16 v[24:27], v[170:173], v[178:181], v[24:27]
	v_mfma_f32_16x16x32_bf16 v[20:23], v[162:165], v[190:193], v[20:23]
	v_mfma_f32_16x16x32_bf16 v[16:19], v[170:173], v[190:193], v[16:19]
	v_mfma_f32_16x16x32_bf16 v[12:15], v[162:165], v[198:201], v[12:15]
	v_mfma_f32_16x16x32_bf16 v[8:11], v[170:173], v[198:201], v[8:11]
	v_mfma_f32_16x16x32_bf16 v[4:7], v[162:165], v[206:209], v[4:7]
	v_mfma_f32_16x16x32_bf16 v[0:3], v[170:173], v[206:209], v[0:3]
	v_mfma_f32_16x16x32_bf16 v[28:31], v[166:169], v[182:185], v[28:31]
	v_mfma_f32_16x16x32_bf16 v[24:27], v[174:177], v[182:185], v[24:27]
	v_mfma_f32_16x16x32_bf16 v[20:23], v[166:169], v[194:197], v[20:23]
	v_mfma_f32_16x16x32_bf16 v[16:19], v[174:177], v[194:197], v[16:19]
	v_mfma_f32_16x16x32_bf16 v[12:15], v[166:169], v[202:205], v[12:15]
	v_mfma_f32_16x16x32_bf16 v[8:11], v[174:177], v[202:205], v[8:11]
	v_mfma_f32_16x16x32_bf16 v[4:7], v[166:169], v[228:231], v[4:7]
	v_mfma_f32_16x16x32_bf16 v[0:3], v[174:177], v[228:231], v[0:3]
	s_barrier
	s_add_i32 s94, s94, 2
	s_add_u32 s72, s72, 0x100
	s_addc_u32 s73, s73, 0
	s_add_u32 s92, s92, 0x100
	s_addc_u32 s93, s93, 0
	s_cmp_gt_u32 s94, 13
	s_cbranch_scc0 .LBB0_164
	s_setprio 0
	s_and_b64 vcc, exec, s[48:49]
	s_cbranch_vccz .LBB0_167
	s_barrier

; #define PG8_STAGE(bufoff, gbase, voff) do { _Pragma("unroll") for (int _i = 0; _i < 2; ++_i) \
;         __builtin_amdgcn_global_load_lds((const unsigned*)((const char*)(gbase) + (voff)[_i]), (PG8_LAS unsigned*)(lds + (bufoff) + ldsw + _i * 8192), 16, 0, 0); } while (0)
; #define PG8_LDA(dst, b, h) do { _Pragma("unroll") for (int m = 0; m < 4; ++m) _Pragma("unroll") for (int k = 0; k < 2; ++k) dst[m][k] = *(const PG8_LAS bf16x8*)(lds + PG8_SA(b, h) + aoff + m * 2048 + k * 1024); } while (0)
; #define PG8_LDB(dst, b, h) do { _Pragma("unroll") for (int n = 0; n < 2; ++n) _Pragma("unroll") for (int k = 0; k < 2; ++k) dst[n][k] = *(const PG8_LAS bf16x8*)(lds + PG8_SB(b, h) + boff + n * 2048 + k * 1024); } while (0)
; #define PG8_MMA(ai, bj, At, Bt) do { __builtin_amdgcn_s_setprio(1); _Pragma("unroll") for (int m = 0; m < 4; ++m) _Pragma("unroll") for (int n = 0; n < 2; ++n) _Pragma("unroll") for (int k = 0; k < 2; ++k) \
;         acc[ai][bj][m][n] = __builtin_amdgcn_mfma_f32_16x16x32_bf16(Bt[n][k], At[m][k], acc[ai][bj][m][n], 0, 0, 0); __builtin_amdgcn_s_setprio(0); } while (0)
; #define PG8_WAIT_V(n) asm volatile("s_waitcnt vmcnt(" #n ")" ::: "memory")
; #define PG8_WAIT_L(n) asm volatile("s_waitcnt lgkmcnt(" #n ")" ::: "memory")
; #define PG8_BAR __builtin_amdgcn_s_barrier()
; #define PG8_SCHED __builtin_amdgcn_sched_barrier(0)
; template <class Epi, class Sched, bool ALIGN_EPI = false, bool SP2 = false>
; __device__ __forceinline__ void gemm_phase(PG8_LAS unsigned char* lds, const Gemm g, const Sched& S, const Epi& E) {
;     ...
;             const bool last = (t == nt - 2);
;             const char* a1 = cA + (size_t)(t + 1) * kstep;
;             const char* a2 = last ? nA : cA + (size_t)(t + 2) * kstep; const char* b2 = last ? nB : cB + (size_t)(t + 2) * kstep;
;             const char* a3 = a2 + kstep; const char* b3 = b2 + kstep;
;             if (last && has_next) S.a_ready(nxt);
;             if constexpr (SP2) {
;             PG8_LDB(B0, 0, 0); PG8_LDB(B1, 0, 1); PG8_SCHED; PG8_LDA(At, 0, 0); PG8_STAGE(PG8_SA(1, 1), a1 + hstep, voffA);
;             PG8_WAIT_V(8); PG8_WAIT_L(0); PG8_BAR; PG8_MMA(0, 0, At, B0); PG8_MMA(0, 1, At, B1); PG8_BAR; PG8_SCHED;
.Lsp_2:
.LBB0_564:
	s_add_u32 s44, vcc_lo, 0xfffc0080
	s_addc_u32 s45, vcc_hi, -1
	s_add_i32 s85, 0, 0x10000
	s_cmp_eq_u32 s84, 12
	s_cselect_b32 s93, s36, s45
	s_cselect_b32 s92, s37, s44
	s_cselect_b32 s59, s67, s94
	s_cselect_b32 s58, s73, s88
	s_add_i32 s8, 0, 0x14000
	v_add_u32_e32 v142, s85, v201
	v_add_u32_e32 v168, s8, v201
	ds_read_b128 v[130:133], v142
	ds_read_b128 v[134:137], v142 offset:1024
	ds_read_b128 v[138:141], v142 offset:2048
	ds_read_b128 v[142:145], v142 offset:3072
	ds_read_b128 v[156:159], v168
	ds_read_b128 v[160:163], v168 offset:1024
	ds_read_b128 v[164:167], v168 offset:2048
	ds_read_b128 v[168:171], v168 offset:3072
	v_lshl_add_u64 v[208:209], vcc, 0, v[152:153]
	s_add_i32 m0, s15, 0xc000
	ds_read_b128 v[172:175], v203
	ds_read_b128 v[176:179], v203 offset:1024
	ds_read_b128 v[180:183], v203 offset:2048
	ds_read_b128 v[184:187], v203 offset:3072
	ds_read_b128 v[188:191], v203 offset:4096
	ds_read_b128 v[192:195], v203 offset:5120
	ds_read_b128 v[196:199], v203 offset:6144
	ds_read_b128 v[204:207], v203 offset:7168
	global_load_lds_dwordx4 v[208:209], off
	v_lshl_add_u64 v[208:209], vcc, 0, v[154:155]
	s_add_i32 m0, s15, 0xe000
	s_nop 0
	global_load_lds_dwordx4 v[208:209], off
	s_waitcnt vmcnt(8)
	s_waitcnt lgkmcnt(0)
	s_barrier
	v_mfma_f32_16x16x32_bf16 v[124:127], v[130:133], v[172:175], v[124:127]
	v_mfma_f32_16x16x32_bf16 v[120:123], v[138:141], v[172:175], v[120:123]
	v_mfma_f32_16x16x32_bf16 v[108:111], v[130:133], v[180:183], v[108:111]
	v_mfma_f32_16x16x32_bf16 v[104:107], v[138:141], v[180:183], v[104:107]
	v_mfma_f32_16x16x32_bf16 v[92:95], v[130:133], v[188:191], v[92:95]
	v_mfma_f32_16x16x32_bf16 v[88:91], v[138:141], v[188:191], v[88:91]
	v_mfma_f32_16x16x32_bf16 v[76:79], v[130:133], v[196:199], v[76:79]
	v_mfma_f32_16x16x32_bf16 v[72:75], v[138:141], v[196:199], v[72:75]
	v_mfma_f32_16x16x32_bf16 v[124:127], v[134:137], v[176:179], v[124:127]
	v_mfma_f32_16x16x32_bf16 v[120:123], v[142:145], v[176:179], v[120:123]
	v_mfma_f32_16x16x32_bf16 v[108:111], v[134:137], v[184:187], v[108:111]
	v_mfma_f32_16x16x32_bf16 v[104:107], v[142:145], v[184:187], v[104:107]
	v_mfma_f32_16x16x32_bf16 v[92:95], v[134:137], v[192:195], v[92:95]
	v_mfma_f32_16x16x32_bf16 v[88:91], v[142:145], v[192:195], v[88:91]
	v_mfma_f32_16x16x32_bf16 v[76:79], v[134:137], v[204:207], v[76:79]
	v_mfma_f32_16x16x32_bf16 v[72:75], v[142:145], v[204:207], v[72:75]
	v_mfma_f32_16x16x32_bf16 v[116:119], v[156:159], v[172:175], v[116:119]
	v_mfma_f32_16x16x32_bf16 v[112:115], v[164:167], v[172:175], v[112:115]
	v_mfma_f32_16x16x32_bf16 v[100:103], v[156:159], v[180:183], v[100:103]
	v_mfma_f32_16x16x32_bf16 v[96:99], v[164:167], v[180:183], v[96:99]
	v_mfma_f32_16x16x32_bf16 v[84:87], v[156:159], v[188:191], v[84:87]
	v_mfma_f32_16x16x32_bf16 v[80:83], v[164:167], v[188:191], v[80:83]
	v_mfma_f32_16x16x32_bf16 v[68:71], v[156:159], v[196:199], v[68:71]
	v_mfma_f32_16x16x32_bf16 v[64:67], v[164:167], v[196:199], v[64:67]
	v_mfma_f32_16x16x32_bf16 v[116:119], v[160:163], v[176:179], v[116:119]
	v_mfma_f32_16x16x32_bf16 v[112:115], v[168:171], v[176:179], v[112:115]
	v_mfma_f32_16x16x32_bf16 v[100:103], v[160:163], v[184:187], v[100:103]
	v_mfma_f32_16x16x32_bf16 v[96:99], v[168:171], v[184:187], v[96:99]
	v_mfma_f32_16x16x32_bf16 v[84:87], v[160:163], v[192:195], v[84:87]
	v_mfma_f32_16x16x32_bf16 v[80:83], v[168:171], v[192:195], v[80:83]
	v_mfma_f32_16x16x32_bf16 v[68:71], v[160:163], v[204:207], v[68:71]
	v_mfma_f32_16x16x32_bf16 v[64:67], v[168:171], v[204:207], v[64:67]
	s_barrier
	s_add_i32 s44, s85, s14
	v_lshl_add_u64 v[208:209], s[58:59], 0, v[128:129]
	s_mov_b32 m0, s44
	ds_read_b128 v[172:175], v203 offset:16384
	ds_read_b128 v[176:179], v203 offset:17408
	ds_read_b128 v[180:183], v203 offset:18432
	ds_read_b128 v[184:187], v203 offset:19456
	ds_read_b128 v[188:191], v203 offset:20480
	ds_read_b128 v[192:195], v203 offset:21504
	ds_read_b128 v[196:199], v203 offset:22528
	ds_read_b128 v[204:207], v203 offset:23552
	global_load_lds_dwordx4 v[208:209], off
	s_add_i32 m0, s44, 0x2000
	s_add_u32 s44, s58, 0x40000
	v_lshl_add_u64 v[210:211], s[58:59], 0, v[146:147]
	s_addc_u32 s45, s59, 0
	s_add_i32 s8, s8, s14
	global_load_lds_dwordx4 v[210:211], off
	v_lshl_add_u64 v[214:215], s[44:45], 0, v[128:129]
	s_mov_b32 m0, s8
	v_lshl_add_u64 v[222:223], s[92:93], 0, v[148:149]
	global_load_lds_dwordx4 v[214:215], off
	v_lshl_add_u64 v[214:215], s[44:45], 0, v[146:147]
	s_add_i32 m0, s8, 0x2000
	s_nop 0
	global_load_lds_dwordx4 v[214:215], off
	v_lshl_add_u64 v[214:215], s[92:93], 0, v[150:151]
	s_mov_b32 m0, s15
	s_nop 0
	global_load_lds_dwordx4 v[214:215], off
	s_mov_b32 m0, s17
	s_nop 0
	global_load_lds_dwordx4 v[222:223], off
	s_waitcnt vmcnt(8)
	s_waitcnt lgkmcnt(0)
	s_barrier
; #define PG8_STAGE(bufoff, gbase, voff) do { _Pragma("unroll") for (int _i = 0; _i < 2; ++_i) \
;         __builtin_amdgcn_global_load_lds((const unsigned*)((const char*)(gbase) + (voff)[_i]), (PG8_LAS unsigned*)(lds + (bufoff) + ldsw + _i * 8192), 16, 0, 0); } while (0)
; #define PG8_LDA(dst, b, h) do { _Pragma("unroll") for (int m = 0; m < 4; ++m) _Pragma("unroll") for (int k = 0; k < 2; ++k) dst[m][k] = *(const PG8_LAS bf16x8*)(lds + PG8_SA(b, h) + aoff + m * 2048 + k * 1024); } while (0)
; #define PG8_LDB(dst, b, h) do { _Pragma("unroll") for (int n = 0; n < 2; ++n) _Pragma("unroll") for (int k = 0; k < 2; ++k) dst[n][k] = *(const PG8_LAS bf16x8*)(lds + PG8_SB(b, h) + boff + n * 2048 + k * 1024); } while (0)
; #define PG8_MMA(ai, bj, At, Bt) do { __builtin_amdgcn_s_setprio(1); _Pragma("unroll") for (int m = 0; m < 4; ++m) _Pragma("unroll") for (int n = 0; n < 2; ++n) _Pragma("unroll") for (int k = 0; k < 2; ++k) \
;         acc[ai][bj][m][n] = __builtin_amdgcn_mfma_f32_16x16x32_bf16(Bt[n][k], At[m][k], acc[ai][bj][m][n], 0, 0, 0); __builtin_amdgcn_s_setprio(0); } while (0)
; #define PG8_WAIT_V(n) asm volatile("s_waitcnt vmcnt(" #n ")" ::: "memory")
; template <class Epi, class Sched, bool ALIGN_EPI = false, bool SP2 = false>
; __device__ __forceinline__ void gemm_phase(PG8_LAS unsigned char* lds, const Gemm g, const Sched& S, const Epi& E) {
;     ...
;             PG8_LDB(B0, 0, 0); PG8_LDB(B1, 0, 1); PG8_SCHED; PG8_LDA(At, 0, 0); PG8_STAGE(PG8_SA(1, 1), a1 + hstep, voffA);
;             PG8_WAIT_V(8); PG8_WAIT_L(0); PG8_BAR; PG8_MMA(0, 0, At, B0); PG8_MMA(0, 1, At, B1); PG8_BAR; PG8_SCHED;
;             PG8_LDA(At, 0, 1); PG8_STAGE(PG8_SB(0, 0), b2, voffB); PG8_STAGE(PG8_SB(0, 1), b2 + hstep, voffB); PG8_STAGE(PG8_SA(0, 0), a2, voffA);
;             PG8_WAIT_V(8); PG8_WAIT_L(0); PG8_BAR; PG8_MMA(1, 0, At, B0); PG8_MMA(1, 1, At, B1); PG8_BAR; PG8_SCHED;
;             PG8_LDB(B0, 1, 0); PG8_LDB(B1, 1, 1); PG8_SCHED; PG8_LDA(At, 1, 0); PG8_STAGE(PG8_SA(0, 1), a2 + hstep, voffA);
;             PG8_WAIT_V(8); PG8_WAIT_L(0); PG8_BAR; PG8_MMA(0, 0, At, B0); PG8_MMA(0, 1, At, B1); PG8_BAR; PG8_SCHED;
;             PG8_LDA(At, 1, 1); PG8_STAGE(PG8_SB(1, 0), b3, voffB); PG8_STAGE(PG8_SB(1, 1), b3 + hstep, voffB); PG8_STAGE(PG8_SA(1, 0), a3, voffA);
;             PG8_WAIT_V(8); PG8_WAIT_L(0); PG8_BAR; PG8_MMA(1, 0, At, B0); PG8_MMA(1, 1, At, B1); PG8_BAR; PG8_SCHED;
	v_mfma_f32_16x16x32_bf16 v[60:63], v[130:133], v[172:175], v[60:63]
	v_mfma_f32_16x16x32_bf16 v[56:59], v[138:141], v[172:175], v[56:59]
	v_mfma_f32_16x16x32_bf16 v[44:47], v[130:133], v[180:183], v[44:47]
	v_mfma_f32_16x16x32_bf16 v[40:43], v[138:141], v[180:183], v[40:43]
	v_mfma_f32_16x16x32_bf16 v[28:31], v[130:133], v[188:191], v[28:31]
	v_mfma_f32_16x16x32_bf16 v[24:27], v[138:141], v[188:191], v[24:27]
	v_mfma_f32_16x16x32_bf16 v[12:15], v[130:133], v[196:199], v[12:15]
	v_mfma_f32_16x16x32_bf16 v[8:11], v[138:141], v[196:199], v[8:11]
	v_mfma_f32_16x16x32_bf16 v[60:63], v[134:137], v[176:179], v[60:63]
	v_mfma_f32_16x16x32_bf16 v[56:59], v[142:145], v[176:179], v[56:59]
	v_mfma_f32_16x16x32_bf16 v[44:47], v[134:137], v[184:187], v[44:47]
	v_mfma_f32_16x16x32_bf16 v[40:43], v[142:145], v[184:187], v[40:43]
	v_mfma_f32_16x16x32_bf16 v[28:31], v[134:137], v[192:195], v[28:31]
	v_mfma_f32_16x16x32_bf16 v[24:27], v[142:145], v[192:195], v[24:27]
	v_mfma_f32_16x16x32_bf16 v[12:15], v[134:137], v[204:207], v[12:15]
	v_mfma_f32_16x16x32_bf16 v[8:11], v[142:145], v[204:207], v[8:11]
	v_mfma_f32_16x16x32_bf16 v[52:55], v[156:159], v[172:175], v[52:55]
	v_mfma_f32_16x16x32_bf16 v[48:51], v[164:167], v[172:175], v[48:51]
	v_mfma_f32_16x16x32_bf16 v[36:39], v[156:159], v[180:183], v[36:39]
	v_mfma_f32_16x16x32_bf16 v[32:35], v[164:167], v[180:183], v[32:35]
	v_mfma_f32_16x16x32_bf16 v[20:23], v[156:159], v[188:191], v[20:23]
	v_mfma_f32_16x16x32_bf16 v[16:19], v[164:167], v[188:191], v[16:19]
	v_mfma_f32_16x16x32_bf16 v[4:7], v[156:159], v[196:199], v[4:7]
	v_mfma_f32_16x16x32_bf16 v[0:3], v[164:167], v[196:199], v[0:3]
	v_mfma_f32_16x16x32_bf16 v[52:55], v[160:163], v[176:179], v[52:55]
	v_mfma_f32_16x16x32_bf16 v[48:51], v[168:171], v[176:179], v[48:51]
	v_mfma_f32_16x16x32_bf16 v[36:39], v[160:163], v[184:187], v[36:39]
	v_mfma_f32_16x16x32_bf16 v[32:35], v[168:171], v[184:187], v[32:35]
	v_mfma_f32_16x16x32_bf16 v[20:23], v[160:163], v[192:195], v[20:23]
	v_mfma_f32_16x16x32_bf16 v[16:19], v[168:171], v[192:195], v[16:19]
	v_mfma_f32_16x16x32_bf16 v[4:7], v[160:163], v[204:207], v[4:7]
	v_mfma_f32_16x16x32_bf16 v[0:3], v[168:171], v[204:207], v[0:3]
	s_barrier
	s_add_i32 s8, 0, 0x18000
	s_add_i32 s85, 0, 0x1c000
	v_add_u32_e32 v142, s8, v201
	v_add_u32_e32 v168, s85, v201
	ds_read_b128 v[130:133], v142
	ds_read_b128 v[134:137], v142 offset:1024
	ds_read_b128 v[138:141], v142 offset:2048
	ds_read_b128 v[142:145], v142 offset:3072
	ds_read_b128 v[156:159], v168
	ds_read_b128 v[160:163], v168 offset:1024
	ds_read_b128 v[164:167], v168 offset:2048
	ds_read_b128 v[168:171], v168 offset:3072
	s_add_u32 s44, s92, 0x40000
	s_addc_u32 s45, s93, 0
	s_mov_b32 m0, s18
	v_lshl_add_u64 v[228:229], s[44:45], 0, v[150:151]
	ds_read_b128 v[172:175], v203 offset:32768
	ds_read_b128 v[176:179], v203 offset:33792
	ds_read_b128 v[180:183], v203 offset:34816
	ds_read_b128 v[184:187], v203 offset:35840
	ds_read_b128 v[188:191], v203 offset:36864
	ds_read_b128 v[192:195], v203 offset:37888
	ds_read_b128 v[196:199], v203 offset:38912
	ds_read_b128 v[204:207], v203 offset:39936
	global_load_lds_dwordx4 v[228:229], off
	v_lshl_add_u64 v[228:229], s[44:45], 0, v[148:149]
	s_mov_b32 m0, s19
	s_nop 0
	global_load_lds_dwordx4 v[228:229], off
	s_waitcnt vmcnt(8)
	s_waitcnt lgkmcnt(0)
	s_barrier
	v_mfma_f32_16x16x32_bf16 v[124:127], v[130:133], v[172:175], v[124:127]
	v_mfma_f32_16x16x32_bf16 v[120:123], v[138:141], v[172:175], v[120:123]
	v_mfma_f32_16x16x32_bf16 v[108:111], v[130:133], v[180:183], v[108:111]
	v_mfma_f32_16x16x32_bf16 v[104:107], v[138:141], v[180:183], v[104:107]
	v_mfma_f32_16x16x32_bf16 v[92:95], v[130:133], v[188:191], v[92:95]
	v_mfma_f32_16x16x32_bf16 v[88:91], v[138:141], v[188:191], v[88:91]
	v_mfma_f32_16x16x32_bf16 v[76:79], v[130:133], v[196:199], v[76:79]
	v_mfma_f32_16x16x32_bf16 v[72:75], v[138:141], v[196:199], v[72:75]
	v_mfma_f32_16x16x32_bf16 v[124:127], v[134:137], v[176:179], v[124:127]
	v_mfma_f32_16x16x32_bf16 v[120:123], v[142:145], v[176:179], v[120:123]
	v_mfma_f32_16x16x32_bf16 v[108:111], v[134:137], v[184:187], v[108:111]
	v_mfma_f32_16x16x32_bf16 v[104:107], v[142:145], v[184:187], v[104:107]
	v_mfma_f32_16x16x32_bf16 v[92:95], v[134:137], v[192:195], v[92:95]
	v_mfma_f32_16x16x32_bf16 v[88:91], v[142:145], v[192:195], v[88:91]
	v_mfma_f32_16x16x32_bf16 v[76:79], v[134:137], v[204:207], v[76:79]
	v_mfma_f32_16x16x32_bf16 v[72:75], v[142:145], v[204:207], v[72:75]
	v_mfma_f32_16x16x32_bf16 v[116:119], v[156:159], v[172:175], v[116:119]
	v_mfma_f32_16x16x32_bf16 v[112:115], v[164:167], v[172:175], v[112:115]
	v_mfma_f32_16x16x32_bf16 v[100:103], v[156:159], v[180:183], v[100:103]
	v_mfma_f32_16x16x32_bf16 v[96:99], v[164:167], v[180:183], v[96:99]
	v_mfma_f32_16x16x32_bf16 v[84:87], v[156:159], v[188:191], v[84:87]
	v_mfma_f32_16x16x32_bf16 v[80:83], v[164:167], v[188:191], v[80:83]
	v_mfma_f32_16x16x32_bf16 v[68:71], v[156:159], v[196:199], v[68:71]
	v_mfma_f32_16x16x32_bf16 v[64:67], v[164:167], v[196:199], v[64:67]
	v_mfma_f32_16x16x32_bf16 v[116:119], v[160:163], v[176:179], v[116:119]
	v_mfma_f32_16x16x32_bf16 v[112:115], v[168:171], v[176:179], v[112:115]
	v_mfma_f32_16x16x32_bf16 v[100:103], v[160:163], v[184:187], v[100:103]
	v_mfma_f32_16x16x32_bf16 v[96:99], v[168:171], v[184:187], v[96:99]
	v_mfma_f32_16x16x32_bf16 v[84:87], v[160:163], v[192:195], v[84:87]
	v_mfma_f32_16x16x32_bf16 v[80:83], v[168:171], v[192:195], v[80:83]
	v_mfma_f32_16x16x32_bf16 v[68:71], v[160:163], v[204:207], v[68:71]
	v_mfma_f32_16x16x32_bf16 v[64:67], v[168:171], v[204:207], v[64:67]
	s_barrier
; #define PG8_STAGE(bufoff, gbase, voff) do { _Pragma("unroll") for (int _i = 0; _i < 2; ++_i) \
;         __builtin_amdgcn_global_load_lds((const unsigned*)((const char*)(gbase) + (voff)[_i]), (PG8_LAS unsigned*)(lds + (bufoff) + ldsw + _i * 8192), 16, 0, 0); } while (0)
; #define PG8_LDA(dst, b, h) do { _Pragma("unroll") for (int m = 0; m < 4; ++m) _Pragma("unroll") for (int k = 0; k < 2; ++k) dst[m][k] = *(const PG8_LAS bf16x8*)(lds + PG8_SA(b, h) + aoff + m * 2048 + k * 1024); } while (0)
; #define PG8_MMA(ai, bj, At, Bt) do { __builtin_amdgcn_s_setprio(1); _Pragma("unroll") for (int m = 0; m < 4; ++m) _Pragma("unroll") for (int n = 0; n < 2; ++n) _Pragma("unroll") for (int k = 0; k < 2; ++k) \
;         acc[ai][bj][m][n] = __builtin_amdgcn_mfma_f32_16x16x32_bf16(Bt[n][k], At[m][k], acc[ai][bj][m][n], 0, 0, 0); __builtin_amdgcn_s_setprio(0); } while (0)
; #define PG8_WAIT_V(n) asm volatile("s_waitcnt vmcnt(" #n ")" ::: "memory")
; #define PG8_WAIT_L(n) asm volatile("s_waitcnt lgkmcnt(" #n ")" ::: "memory")
; #define PG8_BAR __builtin_amdgcn_s_barrier()
; #define PG8_SCHED __builtin_amdgcn_sched_barrier(0)
; template <class Epi, class Sched, bool ALIGN_EPI = false, bool SP2 = false>
; __device__ __forceinline__ void gemm_phase(PG8_LAS unsigned char* lds, const Gemm g, const Sched& S, const Epi& E) {
;     ...
;         for (int t = 0; t < nt; t += 2) {
;             const bool last = (t == nt - 2);
;             const char* a1 = cA + (size_t)(t + 1) * kstep;
;             const char* a2 = last ? nA : cA + (size_t)(t + 2) * kstep; const char* b2 = last ? nB : cB + (size_t)(t + 2) * kstep;
;             const char* a3 = a2 + kstep; const char* b3 = b2 + kstep;
;     ...
;             PG8_LDA(At, 1, 1); PG8_STAGE(PG8_SB(1, 0), b3, voffB); PG8_STAGE(PG8_SB(1, 1), b3 + hstep, voffB); PG8_STAGE(PG8_SA(1, 0), a3, voffA);
;             PG8_WAIT_V(8); PG8_WAIT_L(0); PG8_BAR; PG8_MMA(1, 0, At, B0); PG8_MMA(1, 1, At, B1); PG8_BAR; PG8_SCHED;
	s_add_i32 s8, s8, s14
	v_lshl_add_u64 v[208:209], v[208:209], 0, s[90:91]
	s_mov_b32 m0, s8
	ds_read_b128 v[172:175], v203 offset:49152
	ds_read_b128 v[176:179], v203 offset:50176
	ds_read_b128 v[180:183], v203 offset:51200
	ds_read_b128 v[184:187], v203 offset:52224
	ds_read_b128 v[188:191], v203 offset:53248
	ds_read_b128 v[192:195], v203 offset:54272
	ds_read_b128 v[196:199], v203 offset:55296
	ds_read_b128 v[204:207], v203 offset:56320
	global_load_lds_dwordx4 v[208:209], off
	s_add_i32 m0, s8, 0x2000
	s_add_u32 s44, s58, 0x40080
	v_lshl_add_u64 v[208:209], v[210:211], 0, s[90:91]
	s_addc_u32 s45, s59, 0
	s_add_i32 s8, s85, s14
	global_load_lds_dwordx4 v[208:209], off
	v_lshl_add_u64 v[208:209], s[44:45], 0, v[128:129]
	s_mov_b32 m0, s8
	s_nop 0
	global_load_lds_dwordx4 v[208:209], off
	v_lshl_add_u64 v[208:209], s[44:45], 0, v[146:147]
	s_add_i32 m0, s8, 0x2000
	s_nop 0
	global_load_lds_dwordx4 v[208:209], off
	v_lshl_add_u64 v[208:209], v[214:215], 0, s[90:91]
	s_mov_b32 m0, s30
	s_nop 0
	global_load_lds_dwordx4 v[208:209], off
	v_lshl_add_u64 v[208:209], v[222:223], 0, s[90:91]
	s_mov_b32 m0, s31
	s_nop 0
	global_load_lds_dwordx4 v[208:209], off
	s_waitcnt vmcnt(8)
	s_waitcnt lgkmcnt(0)
	s_barrier
	v_mfma_f32_16x16x32_bf16 v[60:63], v[130:133], v[172:175], v[60:63]
	v_mfma_f32_16x16x32_bf16 v[56:59], v[138:141], v[172:175], v[56:59]
	v_mfma_f32_16x16x32_bf16 v[44:47], v[130:133], v[180:183], v[44:47]
	v_mfma_f32_16x16x32_bf16 v[40:43], v[138:141], v[180:183], v[40:43]
	v_mfma_f32_16x16x32_bf16 v[28:31], v[130:133], v[188:191], v[28:31]
	v_mfma_f32_16x16x32_bf16 v[24:27], v[138:141], v[188:191], v[24:27]
	v_mfma_f32_16x16x32_bf16 v[12:15], v[130:133], v[196:199], v[12:15]
	v_mfma_f32_16x16x32_bf16 v[8:11], v[138:141], v[196:199], v[8:11]
	v_mfma_f32_16x16x32_bf16 v[60:63], v[134:137], v[176:179], v[60:63]
	v_mfma_f32_16x16x32_bf16 v[56:59], v[142:145], v[176:179], v[56:59]
	v_mfma_f32_16x16x32_bf16 v[44:47], v[134:137], v[184:187], v[44:47]
	v_mfma_f32_16x16x32_bf16 v[40:43], v[142:145], v[184:187], v[40:43]
	v_mfma_f32_16x16x32_bf16 v[28:31], v[134:137], v[192:195], v[28:31]
	v_mfma_f32_16x16x32_bf16 v[24:27], v[142:145], v[192:195], v[24:27]
	v_mfma_f32_16x16x32_bf16 v[12:15], v[134:137], v[204:207], v[12:15]
	v_mfma_f32_16x16x32_bf16 v[8:11], v[142:145], v[204:207], v[8:11]
	v_mfma_f32_16x16x32_bf16 v[52:55], v[156:159], v[172:175], v[52:55]
	v_mfma_f32_16x16x32_bf16 v[48:51], v[164:167], v[172:175], v[48:51]
	v_mfma_f32_16x16x32_bf16 v[36:39], v[156:159], v[180:183], v[36:39]
	v_mfma_f32_16x16x32_bf16 v[32:35], v[164:167], v[180:183], v[32:35]
	v_mfma_f32_16x16x32_bf16 v[20:23], v[156:159], v[188:191], v[20:23]
	v_mfma_f32_16x16x32_bf16 v[16:19], v[164:167], v[188:191], v[16:19]
	v_mfma_f32_16x16x32_bf16 v[4:7], v[156:159], v[196:199], v[4:7]
	v_mfma_f32_16x16x32_bf16 v[0:3], v[164:167], v[196:199], v[0:3]
	v_mfma_f32_16x16x32_bf16 v[52:55], v[160:163], v[176:179], v[52:55]
	v_mfma_f32_16x16x32_bf16 v[48:51], v[168:171], v[176:179], v[48:51]
	v_mfma_f32_16x16x32_bf16 v[36:39], v[160:163], v[184:187], v[36:39]
	v_mfma_f32_16x16x32_bf16 v[32:35], v[168:171], v[184:187], v[32:35]
	v_mfma_f32_16x16x32_bf16 v[20:23], v[160:163], v[192:195], v[20:23]
	v_mfma_f32_16x16x32_bf16 v[16:19], v[168:171], v[192:195], v[16:19]
	v_mfma_f32_16x16x32_bf16 v[4:7], v[160:163], v[204:207], v[4:7]
	v_mfma_f32_16x16x32_bf16 v[0:3], v[168:171], v[204:207], v[0:3]
	s_barrier
	s_add_i32 s84, s84, 2
	s_add_u32 vcc_lo, vcc_lo, 0x100
	s_addc_u32 vcc_hi, vcc_hi, 0
	s_add_u32 s88, s88, 0x100
	s_addc_u32 s94, s94, 0
	s_cmp_gt_u32 s84, 13
	s_cbranch_scc0 .LBB0_564
	s_setprio 0
	s_and_b64 vcc, exec, s[62:63]
	s_cbranch_vccz .LBB0_567
	s_barrier

; #define PG8_STAGE(bufoff, gbase, voff) do { _Pragma("unroll") for (int _i = 0; _i < 2; ++_i) \
;         __builtin_amdgcn_global_load_lds((const unsigned*)((const char*)(gbase) + (voff)[_i]), (PG8_LAS unsigned*)(lds + (bufoff) + ldsw + _i * 8192), 16, 0, 0); } while (0)
; #define PG8_LDA(dst, b, h) do { _Pragma("unroll") for (int m = 0; m < 4; ++m) _Pragma("unroll") for (int k = 0; k < 2; ++k) dst[m][k] = *(const PG8_LAS bf16x8*)(lds + PG8_SA(b, h) + aoff + m * 2048 + k * 1024); } while (0)
; #define PG8_LDB(dst, b, h) do { _Pragma("unroll") for (int n = 0; n < 2; ++n) _Pragma("unroll") for (int k = 0; k < 2; ++k) dst[n][k] = *(const PG8_LAS bf16x8*)(lds + PG8_SB(b, h) + boff + n * 2048 + k * 1024); } while (0)
; #define PG8_WAIT_V(n) asm volatile("s_waitcnt vmcnt(" #n ")" ::: "memory")
; #define PG8_WAIT_L(n) asm volatile("s_waitcnt lgkmcnt(" #n ")" ::: "memory")
; #define PG8_BAR __builtin_amdgcn_s_barrier()
; #define PG8_SCHED __builtin_amdgcn_sched_barrier(0)
; template <class Epi, class Sched, bool ALIGN_EPI = false, bool SP2 = false>
; __device__ __forceinline__ void gemm_phase(PG8_LAS unsigned char* lds, const Gemm g, const Sched& S, const Epi& E) {
;     ...
;         const bool has_next = S.next(ui + 1, nxt);
;         const char* nA = has_next ? (const char*)g.A + (size_t)nxt.pm * tstep : cA; const char* nB = has_next ? (const char*)g.Bt + (size_t)nxt.pn * tstep : cB;
;         for (int t = 0; t < nt; t += 2) {
;             const bool last = (t == nt - 2);
;             const char* a1 = cA + (size_t)(t + 1) * kstep;
;             const char* a2 = last ? nA : cA + (size_t)(t + 2) * kstep; const char* b2 = last ? nB : cB + (size_t)(t + 2) * kstep;
;             const char* a3 = a2 + kstep; const char* b3 = b2 + kstep;
;             if (last && has_next) S.a_ready(nxt);
;             if constexpr (SP2) {
;             PG8_LDB(B0, 0, 0); PG8_LDB(B1, 0, 1); PG8_SCHED; PG8_LDA(At, 0, 0); PG8_STAGE(PG8_SA(1, 1), a1 + hstep, voffA);
;             PG8_WAIT_V(8); PG8_WAIT_L(0); PG8_BAR; PG8_MMA(0, 0, At, B0); PG8_MMA(0, 1, At, B1); PG8_BAR; PG8_SCHED;
;             PG8_LDA(At, 0, 1); PG8_STAGE(PG8_SB(0, 0), b2, voffB); PG8_STAGE(PG8_SB(0, 1), b2 + hstep, voffB); PG8_STAGE(PG8_SA(0, 0), a2, voffA);
;             PG8_WAIT_V(8); PG8_WAIT_L(0); PG8_BAR; PG8_MMA(1, 0, At, B0); PG8_MMA(1, 1, At, B1); PG8_BAR; PG8_SCHED;
.Lsp_3:
.LBB0_598:
	s_add_u32 s58, vcc_lo, 0xfffc0080
	s_addc_u32 s59, vcc_hi, -1
	s_add_i32 s84, 0, 0x10000
	s_cmp_eq_u32 s94, 12
	s_cselect_b32 s65, s35, s59
	s_cselect_b32 s64, s36, s58
	s_cselect_b32 s59, s37, s93
	s_cselect_b32 s58, s43, s88
	s_add_i32 s97, 0, 0x14000
	v_add_u32_e32 v76, s84, v228
	v_add_u32_e32 v168, s97, v228
	ds_read_b128 v[64:67], v76
	ds_read_b128 v[68:71], v76 offset:1024
	ds_read_b128 v[72:75], v76 offset:2048
	ds_read_b128 v[76:79], v76 offset:3072
	ds_read_b128 v[156:159], v168
	ds_read_b128 v[160:163], v168 offset:1024
	ds_read_b128 v[164:167], v168 offset:2048
	ds_read_b128 v[168:171], v168 offset:3072
	v_lshl_add_u64 v[204:205], vcc, 0, v[152:153]
	s_add_i32 m0, s18, 0xc000
	ds_read_b128 v[172:175], v230
	ds_read_b128 v[176:179], v230 offset:1024
	ds_read_b128 v[180:183], v230 offset:2048
	ds_read_b128 v[184:187], v230 offset:3072
	ds_read_b128 v[188:191], v230 offset:4096
	ds_read_b128 v[192:195], v230 offset:5120
	ds_read_b128 v[196:199], v230 offset:6144
	ds_read_b128 v[200:203], v230 offset:7168
	global_load_lds_dwordx4 v[204:205], off
	v_lshl_add_u64 v[204:205], vcc, 0, v[154:155]
	s_add_i32 m0, s18, 0xe000
	s_nop 0
	global_load_lds_dwordx4 v[204:205], off
	s_waitcnt vmcnt(8)
	s_waitcnt lgkmcnt(0)
	s_barrier
	v_mfma_f32_16x16x32_bf16 v[142:145], v[64:67], v[172:175], v[142:145]
	v_mfma_f32_16x16x32_bf16 v[138:141], v[72:75], v[172:175], v[138:141]
	v_mfma_f32_16x16x32_bf16 v[134:137], v[64:67], v[180:183], v[134:137]
	v_mfma_f32_16x16x32_bf16 v[124:127], v[72:75], v[180:183], v[124:127]
	v_mfma_f32_16x16x32_bf16 v[108:111], v[64:67], v[188:191], v[108:111]
	v_mfma_f32_16x16x32_bf16 v[104:107], v[72:75], v[188:191], v[104:107]
	v_mfma_f32_16x16x32_bf16 v[100:103], v[64:67], v[196:199], v[100:103]
	v_mfma_f32_16x16x32_bf16 v[92:95], v[72:75], v[196:199], v[92:95]
	v_mfma_f32_16x16x32_bf16 v[142:145], v[68:71], v[176:179], v[142:145]
	v_mfma_f32_16x16x32_bf16 v[138:141], v[76:79], v[176:179], v[138:141]
	v_mfma_f32_16x16x32_bf16 v[134:137], v[68:71], v[184:187], v[134:137]
	v_mfma_f32_16x16x32_bf16 v[124:127], v[76:79], v[184:187], v[124:127]
	v_mfma_f32_16x16x32_bf16 v[108:111], v[68:71], v[192:195], v[108:111]
	v_mfma_f32_16x16x32_bf16 v[104:107], v[76:79], v[192:195], v[104:107]
	v_mfma_f32_16x16x32_bf16 v[100:103], v[68:71], v[200:203], v[100:103]
	v_mfma_f32_16x16x32_bf16 v[92:95], v[76:79], v[200:203], v[92:95]
	v_mfma_f32_16x16x32_bf16 v[130:133], v[156:159], v[172:175], v[130:133]
	v_mfma_f32_16x16x32_bf16 v[120:123], v[164:167], v[172:175], v[120:123]
	v_mfma_f32_16x16x32_bf16 v[116:119], v[156:159], v[180:183], v[116:119]
	v_mfma_f32_16x16x32_bf16 v[112:115], v[164:167], v[180:183], v[112:115]
	v_mfma_f32_16x16x32_bf16 v[96:99], v[156:159], v[188:191], v[96:99]
	v_mfma_f32_16x16x32_bf16 v[88:91], v[164:167], v[188:191], v[88:91]
	v_mfma_f32_16x16x32_bf16 v[84:87], v[156:159], v[196:199], v[84:87]
	v_mfma_f32_16x16x32_bf16 v[80:83], v[164:167], v[196:199], v[80:83]
	v_mfma_f32_16x16x32_bf16 v[130:133], v[160:163], v[176:179], v[130:133]
	v_mfma_f32_16x16x32_bf16 v[120:123], v[168:171], v[176:179], v[120:123]
	v_mfma_f32_16x16x32_bf16 v[116:119], v[160:163], v[184:187], v[116:119]
	v_mfma_f32_16x16x32_bf16 v[112:115], v[168:171], v[184:187], v[112:115]
	v_mfma_f32_16x16x32_bf16 v[96:99], v[160:163], v[192:195], v[96:99]
	v_mfma_f32_16x16x32_bf16 v[88:91], v[168:171], v[192:195], v[88:91]
	v_mfma_f32_16x16x32_bf16 v[84:87], v[160:163], v[200:203], v[84:87]
	v_mfma_f32_16x16x32_bf16 v[80:83], v[168:171], v[200:203], v[80:83]
	s_barrier
	s_add_i32 s84, s84, s17
	v_lshl_add_u64 v[204:205], s[58:59], 0, v[128:129]
	s_mov_b32 m0, s84
	ds_read_b128 v[172:175], v230 offset:16384
	ds_read_b128 v[176:179], v230 offset:17408
	ds_read_b128 v[180:183], v230 offset:18432
	ds_read_b128 v[184:187], v230 offset:19456
	ds_read_b128 v[188:191], v230 offset:20480
	ds_read_b128 v[192:195], v230 offset:21504
	ds_read_b128 v[196:199], v230 offset:22528
	ds_read_b128 v[200:203], v230 offset:23552
	global_load_lds_dwordx4 v[204:205], off
	s_add_i32 m0, s84, 0x2000
	s_add_u32 s84, s58, 0x40000
	v_lshl_add_u64 v[206:207], s[58:59], 0, v[146:147]
	s_addc_u32 s85, s59, 0
	s_add_i32 s97, s97, s17
	global_load_lds_dwordx4 v[206:207], off
	v_lshl_add_u64 v[208:209], s[84:85], 0, v[128:129]
	s_mov_b32 m0, s97
	v_lshl_add_u64 v[210:211], s[64:65], 0, v[148:149]
	global_load_lds_dwordx4 v[208:209], off
	v_lshl_add_u64 v[208:209], s[84:85], 0, v[146:147]
	s_add_i32 m0, s97, 0x2000
	s_nop 0
	global_load_lds_dwordx4 v[208:209], off
	v_lshl_add_u64 v[208:209], s[64:65], 0, v[150:151]
	s_mov_b32 m0, s18
	s_nop 0
	global_load_lds_dwordx4 v[208:209], off
	s_mov_b32 m0, s19
	s_nop 0
	global_load_lds_dwordx4 v[210:211], off
	s_waitcnt vmcnt(8)
	s_waitcnt lgkmcnt(0)
	s_barrier
; #define PG8_STAGE(bufoff, gbase, voff) do { _Pragma("unroll") for (int _i = 0; _i < 2; ++_i) \
;         __builtin_amdgcn_global_load_lds((const unsigned*)((const char*)(gbase) + (voff)[_i]), (PG8_LAS unsigned*)(lds + (bufoff) + ldsw + _i * 8192), 16, 0, 0); } while (0)
; #define PG8_LDA(dst, b, h) do { _Pragma("unroll") for (int m = 0; m < 4; ++m) _Pragma("unroll") for (int k = 0; k < 2; ++k) dst[m][k] = *(const PG8_LAS bf16x8*)(lds + PG8_SA(b, h) + aoff + m * 2048 + k * 1024); } while (0)
; #define PG8_LDB(dst, b, h) do { _Pragma("unroll") for (int n = 0; n < 2; ++n) _Pragma("unroll") for (int k = 0; k < 2; ++k) dst[n][k] = *(const PG8_LAS bf16x8*)(lds + PG8_SB(b, h) + boff + n * 2048 + k * 1024); } while (0)
; #define PG8_MMA(ai, bj, At, Bt) do { __builtin_amdgcn_s_setprio(1); _Pragma("unroll") for (int m = 0; m < 4; ++m) _Pragma("unroll") for (int n = 0; n < 2; ++n) _Pragma("unroll") for (int k = 0; k < 2; ++k) \
;         acc[ai][bj][m][n] = __builtin_amdgcn_mfma_f32_16x16x32_bf16(Bt[n][k], At[m][k], acc[ai][bj][m][n], 0, 0, 0); __builtin_amdgcn_s_setprio(0); } while (0)
; #define PG8_WAIT_V(n) asm volatile("s_waitcnt vmcnt(" #n ")" ::: "memory")
; #define PG8_WAIT_L(n) asm volatile("s_waitcnt lgkmcnt(" #n ")" ::: "memory")
; #define PG8_BAR __builtin_amdgcn_s_barrier()
; #define PG8_SCHED __builtin_amdgcn_sched_barrier(0)
; template <class Epi, class Sched, bool ALIGN_EPI = false, bool SP2 = false>
; __device__ __forceinline__ void gemm_phase(PG8_LAS unsigned char* lds, const Gemm g, const Sched& S, const Epi& E) {
;     ...
;             PG8_LDA(At, 0, 1); PG8_STAGE(PG8_SB(0, 0), b2, voffB); PG8_STAGE(PG8_SB(0, 1), b2 + hstep, voffB); PG8_STAGE(PG8_SA(0, 0), a2, voffA);
;             PG8_WAIT_V(8); PG8_WAIT_L(0); PG8_BAR; PG8_MMA(1, 0, At, B0); PG8_MMA(1, 1, At, B1); PG8_BAR; PG8_SCHED;
;             PG8_LDB(B0, 1, 0); PG8_LDB(B1, 1, 1); PG8_SCHED; PG8_LDA(At, 1, 0); PG8_STAGE(PG8_SA(0, 1), a2 + hstep, voffA);
;             PG8_WAIT_V(8); PG8_WAIT_L(0); PG8_BAR; PG8_MMA(0, 0, At, B0); PG8_MMA(0, 1, At, B1); PG8_BAR; PG8_SCHED;
	v_mfma_f32_16x16x32_bf16 v[60:63], v[64:67], v[172:175], v[60:63]
	v_mfma_f32_16x16x32_bf16 v[56:59], v[72:75], v[172:175], v[56:59]
	v_mfma_f32_16x16x32_bf16 v[52:55], v[64:67], v[180:183], v[52:55]
	v_mfma_f32_16x16x32_bf16 v[44:47], v[72:75], v[180:183], v[44:47]
	v_mfma_f32_16x16x32_bf16 v[28:31], v[64:67], v[188:191], v[28:31]
	v_mfma_f32_16x16x32_bf16 v[24:27], v[72:75], v[188:191], v[24:27]
	v_mfma_f32_16x16x32_bf16 v[12:15], v[64:67], v[196:199], v[12:15]
	v_mfma_f32_16x16x32_bf16 v[8:11], v[72:75], v[196:199], v[8:11]
	v_mfma_f32_16x16x32_bf16 v[60:63], v[68:71], v[176:179], v[60:63]
	v_mfma_f32_16x16x32_bf16 v[56:59], v[76:79], v[176:179], v[56:59]
	v_mfma_f32_16x16x32_bf16 v[52:55], v[68:71], v[184:187], v[52:55]
	v_mfma_f32_16x16x32_bf16 v[44:47], v[76:79], v[184:187], v[44:47]
	v_mfma_f32_16x16x32_bf16 v[28:31], v[68:71], v[192:195], v[28:31]
	v_mfma_f32_16x16x32_bf16 v[24:27], v[76:79], v[192:195], v[24:27]
	v_mfma_f32_16x16x32_bf16 v[12:15], v[68:71], v[200:203], v[12:15]
	v_mfma_f32_16x16x32_bf16 v[8:11], v[76:79], v[200:203], v[8:11]
	v_mfma_f32_16x16x32_bf16 v[48:51], v[156:159], v[172:175], v[48:51]
	v_mfma_f32_16x16x32_bf16 v[40:43], v[164:167], v[172:175], v[40:43]
	v_mfma_f32_16x16x32_bf16 v[36:39], v[156:159], v[180:183], v[36:39]
	v_mfma_f32_16x16x32_bf16 v[32:35], v[164:167], v[180:183], v[32:35]
	v_mfma_f32_16x16x32_bf16 v[20:23], v[156:159], v[188:191], v[20:23]
	v_mfma_f32_16x16x32_bf16 v[16:19], v[164:167], v[188:191], v[16:19]
	v_mfma_f32_16x16x32_bf16 v[4:7], v[156:159], v[196:199], v[4:7]
	v_mfma_f32_16x16x32_bf16 v[0:3], v[164:167], v[196:199], v[0:3]
	v_mfma_f32_16x16x32_bf16 v[48:51], v[160:163], v[176:179], v[48:51]
	v_mfma_f32_16x16x32_bf16 v[40:43], v[168:171], v[176:179], v[40:43]
	v_mfma_f32_16x16x32_bf16 v[36:39], v[160:163], v[184:187], v[36:39]
	v_mfma_f32_16x16x32_bf16 v[32:35], v[168:171], v[184:187], v[32:35]
	v_mfma_f32_16x16x32_bf16 v[20:23], v[160:163], v[192:195], v[20:23]
	v_mfma_f32_16x16x32_bf16 v[16:19], v[168:171], v[192:195], v[16:19]
	v_mfma_f32_16x16x32_bf16 v[4:7], v[160:163], v[200:203], v[4:7]
	v_mfma_f32_16x16x32_bf16 v[0:3], v[168:171], v[200:203], v[0:3]
	s_barrier
	s_add_i32 s84, 0, 0x18000
	s_add_i32 s85, 0, 0x1c000
	v_add_u32_e32 v76, s84, v228
	v_add_u32_e32 v168, s85, v228
	ds_read_b128 v[64:67], v76
	ds_read_b128 v[68:71], v76 offset:1024
	ds_read_b128 v[72:75], v76 offset:2048
	ds_read_b128 v[76:79], v76 offset:3072
	ds_read_b128 v[156:159], v168
	ds_read_b128 v[160:163], v168 offset:1024
	ds_read_b128 v[164:167], v168 offset:2048
	ds_read_b128 v[168:171], v168 offset:3072
	s_add_u32 s64, s64, 0x40000
	s_addc_u32 s65, s65, 0
	s_mov_b32 m0, s20
	v_lshl_add_u64 v[214:215], s[64:65], 0, v[150:151]
	ds_read_b128 v[172:175], v230 offset:32768
	ds_read_b128 v[176:179], v230 offset:33792
	ds_read_b128 v[180:183], v230 offset:34816
	ds_read_b128 v[184:187], v230 offset:35840
	ds_read_b128 v[188:191], v230 offset:36864
	ds_read_b128 v[192:195], v230 offset:37888
	ds_read_b128 v[196:199], v230 offset:38912
	ds_read_b128 v[200:203], v230 offset:39936
	global_load_lds_dwordx4 v[214:215], off
	v_lshl_add_u64 v[214:215], s[64:65], 0, v[148:149]
	s_mov_b32 m0, s21
	s_nop 0
	global_load_lds_dwordx4 v[214:215], off
	s_waitcnt vmcnt(8)
	s_waitcnt lgkmcnt(0)
	s_barrier
	v_mfma_f32_16x16x32_bf16 v[142:145], v[64:67], v[172:175], v[142:145]
	v_mfma_f32_16x16x32_bf16 v[138:141], v[72:75], v[172:175], v[138:141]
	v_mfma_f32_16x16x32_bf16 v[134:137], v[64:67], v[180:183], v[134:137]
	v_mfma_f32_16x16x32_bf16 v[124:127], v[72:75], v[180:183], v[124:127]
	v_mfma_f32_16x16x32_bf16 v[108:111], v[64:67], v[188:191], v[108:111]
	v_mfma_f32_16x16x32_bf16 v[104:107], v[72:75], v[188:191], v[104:107]
	v_mfma_f32_16x16x32_bf16 v[100:103], v[64:67], v[196:199], v[100:103]
	v_mfma_f32_16x16x32_bf16 v[92:95], v[72:75], v[196:199], v[92:95]
	v_mfma_f32_16x16x32_bf16 v[142:145], v[68:71], v[176:179], v[142:145]
	v_mfma_f32_16x16x32_bf16 v[138:141], v[76:79], v[176:179], v[138:141]
	v_mfma_f32_16x16x32_bf16 v[134:137], v[68:71], v[184:187], v[134:137]
	v_mfma_f32_16x16x32_bf16 v[124:127], v[76:79], v[184:187], v[124:127]
	v_mfma_f32_16x16x32_bf16 v[108:111], v[68:71], v[192:195], v[108:111]
	v_mfma_f32_16x16x32_bf16 v[104:107], v[76:79], v[192:195], v[104:107]
	v_mfma_f32_16x16x32_bf16 v[100:103], v[68:71], v[200:203], v[100:103]
	v_mfma_f32_16x16x32_bf16 v[92:95], v[76:79], v[200:203], v[92:95]
	v_mfma_f32_16x16x32_bf16 v[130:133], v[156:159], v[172:175], v[130:133]
	v_mfma_f32_16x16x32_bf16 v[120:123], v[164:167], v[172:175], v[120:123]
	v_mfma_f32_16x16x32_bf16 v[116:119], v[156:159], v[180:183], v[116:119]
	v_mfma_f32_16x16x32_bf16 v[112:115], v[164:167], v[180:183], v[112:115]
	v_mfma_f32_16x16x32_bf16 v[96:99], v[156:159], v[188:191], v[96:99]
	v_mfma_f32_16x16x32_bf16 v[88:91], v[164:167], v[188:191], v[88:91]
	v_mfma_f32_16x16x32_bf16 v[84:87], v[156:159], v[196:199], v[84:87]
	v_mfma_f32_16x16x32_bf16 v[80:83], v[164:167], v[196:199], v[80:83]
	v_mfma_f32_16x16x32_bf16 v[130:133], v[160:163], v[176:179], v[130:133]
	v_mfma_f32_16x16x32_bf16 v[120:123], v[168:171], v[176:179], v[120:123]
	v_mfma_f32_16x16x32_bf16 v[116:119], v[160:163], v[184:187], v[116:119]
	v_mfma_f32_16x16x32_bf16 v[112:115], v[168:171], v[184:187], v[112:115]
	v_mfma_f32_16x16x32_bf16 v[96:99], v[160:163], v[192:195], v[96:99]
	v_mfma_f32_16x16x32_bf16 v[88:91], v[168:171], v[192:195], v[88:91]
	v_mfma_f32_16x16x32_bf16 v[84:87], v[160:163], v[200:203], v[84:87]
	v_mfma_f32_16x16x32_bf16 v[80:83], v[168:171], v[200:203], v[80:83]
	s_barrier
; #define PG8_STAGE(bufoff, gbase, voff) do { _Pragma("unroll") for (int _i = 0; _i < 2; ++_i) \
;         __builtin_amdgcn_global_load_lds((const unsigned*)((const char*)(gbase) + (voff)[_i]), (PG8_LAS unsigned*)(lds + (bufoff) + ldsw + _i * 8192), 16, 0, 0); } while (0)
; #define PG8_LDA(dst, b, h) do { _Pragma("unroll") for (int m = 0; m < 4; ++m) _Pragma("unroll") for (int k = 0; k < 2; ++k) dst[m][k] = *(const PG8_LAS bf16x8*)(lds + PG8_SA(b, h) + aoff + m * 2048 + k * 1024); } while (0)
; #define PG8_MMA(ai, bj, At, Bt) do { __builtin_amdgcn_s_setprio(1); _Pragma("unroll") for (int m = 0; m < 4; ++m) _Pragma("unroll") for (int n = 0; n < 2; ++n) _Pragma("unroll") for (int k = 0; k < 2; ++k) \
;         acc[ai][bj][m][n] = __builtin_amdgcn_mfma_f32_16x16x32_bf16(Bt[n][k], At[m][k], acc[ai][bj][m][n], 0, 0, 0); __builtin_amdgcn_s_setprio(0); } while (0)
; #define PG8_WAIT_V(n) asm volatile("s_waitcnt vmcnt(" #n ")" ::: "memory")
; #define PG8_WAIT_L(n) asm volatile("s_waitcnt lgkmcnt(" #n ")" ::: "memory")
; #define PG8_BAR __builtin_amdgcn_s_barrier()
; #define PG8_SCHED __builtin_amdgcn_sched_barrier(0)
; template <class Epi, class Sched, bool ALIGN_EPI = false, bool SP2 = false>
; __device__ __forceinline__ void gemm_phase(PG8_LAS unsigned char* lds, const Gemm g, const Sched& S, const Epi& E) {
;     ...
;         for (int t = 0; t < nt; t += 2) {
;             const bool last = (t == nt - 2);
;             const char* a1 = cA + (size_t)(t + 1) * kstep;
;             const char* a2 = last ? nA : cA + (size_t)(t + 2) * kstep; const char* b2 = last ? nB : cB + (size_t)(t + 2) * kstep;
;             const char* a3 = a2 + kstep; const char* b3 = b2 + kstep;
;     ...
;             PG8_LDA(At, 1, 1); PG8_STAGE(PG8_SB(1, 0), b3, voffB); PG8_STAGE(PG8_SB(1, 1), b3 + hstep, voffB); PG8_STAGE(PG8_SA(1, 0), a3, voffA);
;             PG8_WAIT_V(8); PG8_WAIT_L(0); PG8_BAR; PG8_MMA(1, 0, At, B0); PG8_MMA(1, 1, At, B1); PG8_BAR; PG8_SCHED;
	s_add_i32 s64, s84, s17
	v_lshl_add_u64 v[204:205], v[204:205], 0, s[90:91]
	s_mov_b32 m0, s64
	ds_read_b128 v[172:175], v230 offset:49152
	ds_read_b128 v[176:179], v230 offset:50176
	ds_read_b128 v[180:183], v230 offset:51200
	ds_read_b128 v[184:187], v230 offset:52224
	ds_read_b128 v[188:191], v230 offset:53248
	ds_read_b128 v[192:195], v230 offset:54272
	ds_read_b128 v[196:199], v230 offset:55296
	ds_read_b128 v[200:203], v230 offset:56320
	global_load_lds_dwordx4 v[204:205], off
	s_add_i32 m0, s64, 0x2000
	s_add_u32 s58, s58, 0x40080
	v_lshl_add_u64 v[204:205], v[206:207], 0, s[90:91]
	s_addc_u32 s59, s59, 0
	s_add_i32 s64, s85, s17
	global_load_lds_dwordx4 v[204:205], off
	v_lshl_add_u64 v[204:205], s[58:59], 0, v[128:129]
	s_mov_b32 m0, s64
	s_nop 0
	global_load_lds_dwordx4 v[204:205], off
	v_lshl_add_u64 v[204:205], s[58:59], 0, v[146:147]
	s_add_i32 m0, s64, 0x2000
	s_nop 0
	global_load_lds_dwordx4 v[204:205], off
	v_lshl_add_u64 v[204:205], v[208:209], 0, s[90:91]
	s_mov_b32 m0, s28
	s_nop 0
	global_load_lds_dwordx4 v[204:205], off
	v_lshl_add_u64 v[204:205], v[210:211], 0, s[90:91]
	s_mov_b32 m0, s29
	s_nop 0
	global_load_lds_dwordx4 v[204:205], off
	s_waitcnt vmcnt(8)
	s_waitcnt lgkmcnt(0)
	s_barrier
	v_mfma_f32_16x16x32_bf16 v[60:63], v[64:67], v[172:175], v[60:63]
	v_mfma_f32_16x16x32_bf16 v[56:59], v[72:75], v[172:175], v[56:59]
	v_mfma_f32_16x16x32_bf16 v[52:55], v[64:67], v[180:183], v[52:55]
	v_mfma_f32_16x16x32_bf16 v[44:47], v[72:75], v[180:183], v[44:47]
	v_mfma_f32_16x16x32_bf16 v[28:31], v[64:67], v[188:191], v[28:31]
	v_mfma_f32_16x16x32_bf16 v[24:27], v[72:75], v[188:191], v[24:27]
	v_mfma_f32_16x16x32_bf16 v[12:15], v[64:67], v[196:199], v[12:15]
	v_mfma_f32_16x16x32_bf16 v[8:11], v[72:75], v[196:199], v[8:11]
	v_mfma_f32_16x16x32_bf16 v[60:63], v[68:71], v[176:179], v[60:63]
	v_mfma_f32_16x16x32_bf16 v[56:59], v[76:79], v[176:179], v[56:59]
	v_mfma_f32_16x16x32_bf16 v[52:55], v[68:71], v[184:187], v[52:55]
	v_mfma_f32_16x16x32_bf16 v[44:47], v[76:79], v[184:187], v[44:47]
	v_mfma_f32_16x16x32_bf16 v[28:31], v[68:71], v[192:195], v[28:31]
	v_mfma_f32_16x16x32_bf16 v[24:27], v[76:79], v[192:195], v[24:27]
	v_mfma_f32_16x16x32_bf16 v[12:15], v[68:71], v[200:203], v[12:15]
	v_mfma_f32_16x16x32_bf16 v[8:11], v[76:79], v[200:203], v[8:11]
	v_mfma_f32_16x16x32_bf16 v[48:51], v[156:159], v[172:175], v[48:51]
	v_mfma_f32_16x16x32_bf16 v[40:43], v[164:167], v[172:175], v[40:43]
	v_mfma_f32_16x16x32_bf16 v[36:39], v[156:159], v[180:183], v[36:39]
	v_mfma_f32_16x16x32_bf16 v[32:35], v[164:167], v[180:183], v[32:35]
	v_mfma_f32_16x16x32_bf16 v[20:23], v[156:159], v[188:191], v[20:23]
	v_mfma_f32_16x16x32_bf16 v[16:19], v[164:167], v[188:191], v[16:19]
	v_mfma_f32_16x16x32_bf16 v[4:7], v[156:159], v[196:199], v[4:7]
	v_mfma_f32_16x16x32_bf16 v[0:3], v[164:167], v[196:199], v[0:3]
	v_mfma_f32_16x16x32_bf16 v[48:51], v[160:163], v[176:179], v[48:51]
	v_mfma_f32_16x16x32_bf16 v[40:43], v[168:171], v[176:179], v[40:43]
	v_mfma_f32_16x16x32_bf16 v[36:39], v[160:163], v[184:187], v[36:39]
	v_mfma_f32_16x16x32_bf16 v[32:35], v[168:171], v[184:187], v[32:35]
	v_mfma_f32_16x16x32_bf16 v[20:23], v[160:163], v[192:195], v[20:23]
	v_mfma_f32_16x16x32_bf16 v[16:19], v[168:171], v[192:195], v[16:19]
	v_mfma_f32_16x16x32_bf16 v[4:7], v[160:163], v[200:203], v[4:7]
	v_mfma_f32_16x16x32_bf16 v[0:3], v[168:171], v[200:203], v[0:3]
	s_barrier
	s_add_i32 s94, s94, 2
	s_add_u32 vcc_lo, vcc_lo, 0x100
	s_addc_u32 vcc_hi, vcc_hi, 0
	s_add_u32 s88, s88, 0x100
	s_addc_u32 s93, s93, 0
	s_cmp_gt_u32 s94, 13
	s_cbranch_scc0 .LBB0_598
	s_setprio 0
	s_and_b64 vcc, exec, s[72:73]
	s_cbranch_vccz .LBB0_601
	s_barrier

; #define PG8_STAGE(bufoff, gbase, voff) do { _Pragma("unroll") for (int _i = 0; _i < 2; ++_i) \
;         __builtin_amdgcn_global_load_lds((const unsigned*)((const char*)(gbase) + (voff)[_i]), (PG8_LAS unsigned*)(lds + (bufoff) + ldsw + _i * 8192), 16, 0, 0); } while (0)
; #define PG8_LDA(dst, b, h) do { _Pragma("unroll") for (int m = 0; m < 4; ++m) _Pragma("unroll") for (int k = 0; k < 2; ++k) dst[m][k] = *(const PG8_LAS bf16x8*)(lds + PG8_SA(b, h) + aoff + m * 2048 + k * 1024); } while (0)
; #define PG8_LDB(dst, b, h) do { _Pragma("unroll") for (int n = 0; n < 2; ++n) _Pragma("unroll") for (int k = 0; k < 2; ++k) dst[n][k] = *(const PG8_LAS bf16x8*)(lds + PG8_SB(b, h) + boff + n * 2048 + k * 1024); } while (0)
; #define PG8_WAIT_V(n) asm volatile("s_waitcnt vmcnt(" #n ")" ::: "memory")
; #define PG8_WAIT_L(n) asm volatile("s_waitcnt lgkmcnt(" #n ")" ::: "memory")
; #define PG8_BAR __builtin_amdgcn_s_barrier()
; #define PG8_SCHED __builtin_amdgcn_sched_barrier(0)
; template <class Epi, class Sched, bool ALIGN_EPI = false, bool SP2 = false>
; __device__ __forceinline__ void gemm_phase(PG8_LAS unsigned char* lds, const Gemm g, const Sched& S, const Epi& E) {
;     ...
;         const bool has_next = S.next(ui + 1, nxt);
;         const char* nA = has_next ? (const char*)g.A + (size_t)nxt.pm * tstep : cA; const char* nB = has_next ? (const char*)g.Bt + (size_t)nxt.pn * tstep : cB;
;         for (int t = 0; t < nt; t += 2) {
;             const bool last = (t == nt - 2);
;             const char* a1 = cA + (size_t)(t + 1) * kstep;
;             const char* a2 = last ? nA : cA + (size_t)(t + 2) * kstep; const char* b2 = last ? nB : cB + (size_t)(t + 2) * kstep;
;             const char* a3 = a2 + kstep; const char* b3 = b2 + kstep;
;             if (last && has_next) S.a_ready(nxt);
;             if constexpr (SP2) {
;             PG8_LDB(B0, 0, 0); PG8_LDB(B1, 0, 1); PG8_SCHED; PG8_LDA(At, 0, 0); PG8_STAGE(PG8_SA(1, 1), a1 + hstep, voffA);
;             PG8_WAIT_V(8); PG8_WAIT_L(0); PG8_BAR; PG8_MMA(0, 0, At, B0); PG8_MMA(0, 1, At, B1); PG8_BAR; PG8_SCHED;
;             PG8_LDA(At, 0, 1); PG8_STAGE(PG8_SB(0, 0), b2, voffB); PG8_STAGE(PG8_SB(0, 1), b2 + hstep, voffB); PG8_STAGE(PG8_SA(0, 0), a2, voffA);
;             PG8_WAIT_V(8); PG8_WAIT_L(0); PG8_BAR; PG8_MMA(1, 0, At, B0); PG8_MMA(1, 1, At, B1); PG8_BAR; PG8_SCHED;
.Lsp_0:
.LBB0_813:
	s_add_u32 s8, s66, 0xfffc0080
	s_addc_u32 s37, s67, -1
	s_add_i32 s49, 0, 0x10000
	s_cmp_eq_u32 s36, 12
	s_cselect_b32 s65, s28, s37
	s_cselect_b32 s64, s29, s8
	s_cselect_b32 s59, s30, s35
	s_cselect_b32 s58, s31, s34
	s_add_i32 s8, 0, 0x14000
	v_add_u32_e32 v156, s49, v145
	v_add_u32_e32 v172, s8, v145
	ds_read_b128 v[140:143], v156
	ds_read_b128 v[148:151], v156 offset:1024
	ds_read_b128 v[152:155], v156 offset:2048
	ds_read_b128 v[156:159], v156 offset:3072
	ds_read_b128 v[160:163], v172
	ds_read_b128 v[164:167], v172 offset:1024
	ds_read_b128 v[168:171], v172 offset:2048
	ds_read_b128 v[172:175], v172 offset:3072
	v_lshl_add_u64 v[208:209], s[66:67], 0, v[136:137]
	s_add_i32 m0, s18, 0xc000
	ds_read_b128 v[176:179], v147
	ds_read_b128 v[180:183], v147 offset:1024
	ds_read_b128 v[184:187], v147 offset:2048
	ds_read_b128 v[188:191], v147 offset:3072
	ds_read_b128 v[192:195], v147 offset:4096
	ds_read_b128 v[196:199], v147 offset:5120
	ds_read_b128 v[200:203], v147 offset:6144
	ds_read_b128 v[204:207], v147 offset:7168
	global_load_lds_dwordx4 v[208:209], off
	v_lshl_add_u64 v[208:209], s[66:67], 0, v[138:139]
	s_add_i32 m0, s18, 0xe000
	s_nop 0
	global_load_lds_dwordx4 v[208:209], off
	s_waitcnt vmcnt(8)
	s_waitcnt lgkmcnt(0)
	s_barrier
	v_mfma_f32_16x16x32_bf16 v[124:127], v[140:143], v[176:179], v[124:127]
	v_mfma_f32_16x16x32_bf16 v[116:119], v[152:155], v[176:179], v[116:119]
	v_mfma_f32_16x16x32_bf16 v[108:111], v[140:143], v[184:187], v[108:111]
	v_mfma_f32_16x16x32_bf16 v[100:103], v[152:155], v[184:187], v[100:103]
	v_mfma_f32_16x16x32_bf16 v[92:95], v[140:143], v[192:195], v[92:95]
	v_mfma_f32_16x16x32_bf16 v[84:87], v[152:155], v[192:195], v[84:87]
	v_mfma_f32_16x16x32_bf16 v[76:79], v[140:143], v[200:203], v[76:79]
	v_mfma_f32_16x16x32_bf16 v[68:71], v[152:155], v[200:203], v[68:71]
	v_mfma_f32_16x16x32_bf16 v[124:127], v[148:151], v[180:183], v[124:127]
	v_mfma_f32_16x16x32_bf16 v[116:119], v[156:159], v[180:183], v[116:119]
	v_mfma_f32_16x16x32_bf16 v[108:111], v[148:151], v[188:191], v[108:111]
	v_mfma_f32_16x16x32_bf16 v[100:103], v[156:159], v[188:191], v[100:103]
	v_mfma_f32_16x16x32_bf16 v[92:95], v[148:151], v[196:199], v[92:95]
	v_mfma_f32_16x16x32_bf16 v[84:87], v[156:159], v[196:199], v[84:87]
	v_mfma_f32_16x16x32_bf16 v[76:79], v[148:151], v[204:207], v[76:79]
	v_mfma_f32_16x16x32_bf16 v[68:71], v[156:159], v[204:207], v[68:71]
	v_mfma_f32_16x16x32_bf16 v[120:123], v[160:163], v[176:179], v[120:123]
	v_mfma_f32_16x16x32_bf16 v[112:115], v[168:171], v[176:179], v[112:115]
	v_mfma_f32_16x16x32_bf16 v[104:107], v[160:163], v[184:187], v[104:107]
	v_mfma_f32_16x16x32_bf16 v[96:99], v[168:171], v[184:187], v[96:99]
	v_mfma_f32_16x16x32_bf16 v[88:91], v[160:163], v[192:195], v[88:91]
	v_mfma_f32_16x16x32_bf16 v[80:83], v[168:171], v[192:195], v[80:83]
	v_mfma_f32_16x16x32_bf16 v[72:75], v[160:163], v[200:203], v[72:75]
	v_mfma_f32_16x16x32_bf16 v[64:67], v[168:171], v[200:203], v[64:67]
	v_mfma_f32_16x16x32_bf16 v[120:123], v[164:167], v[180:183], v[120:123]
	v_mfma_f32_16x16x32_bf16 v[112:115], v[172:175], v[180:183], v[112:115]
	v_mfma_f32_16x16x32_bf16 v[104:107], v[164:167], v[188:191], v[104:107]
	v_mfma_f32_16x16x32_bf16 v[96:99], v[172:175], v[188:191], v[96:99]
	v_mfma_f32_16x16x32_bf16 v[88:91], v[164:167], v[196:199], v[88:91]
	v_mfma_f32_16x16x32_bf16 v[80:83], v[172:175], v[196:199], v[80:83]
	v_mfma_f32_16x16x32_bf16 v[72:75], v[164:167], v[204:207], v[72:75]
	v_mfma_f32_16x16x32_bf16 v[64:67], v[172:175], v[204:207], v[64:67]
	s_barrier
	s_add_i32 s37, s49, s17
	v_lshl_add_u64 v[208:209], s[58:59], 0, v[128:129]
	s_mov_b32 m0, s37
	ds_read_b128 v[176:179], v147 offset:16384
	ds_read_b128 v[180:183], v147 offset:17408
	ds_read_b128 v[184:187], v147 offset:18432
	ds_read_b128 v[188:191], v147 offset:19456
	ds_read_b128 v[192:195], v147 offset:20480
	ds_read_b128 v[196:199], v147 offset:21504
	ds_read_b128 v[200:203], v147 offset:22528
	ds_read_b128 v[204:207], v147 offset:23552
	global_load_lds_dwordx4 v[208:209], off
	s_add_i32 m0, s37, 0x2000
	s_add_u32 s72, s58, 0x40000
	v_lshl_add_u64 v[210:211], s[58:59], 0, v[130:131]
	s_addc_u32 s73, s59, 0
	s_add_i32 s8, s8, s17
	global_load_lds_dwordx4 v[210:211], off
	v_lshl_add_u64 v[214:215], s[72:73], 0, v[128:129]
	s_mov_b32 m0, s8
	v_lshl_add_u64 v[222:223], s[64:65], 0, v[132:133]
	global_load_lds_dwordx4 v[214:215], off
	v_lshl_add_u64 v[214:215], s[72:73], 0, v[130:131]
	s_add_i32 m0, s8, 0x2000
	s_nop 0
	global_load_lds_dwordx4 v[214:215], off
	v_lshl_add_u64 v[214:215], s[64:65], 0, v[134:135]
	s_mov_b32 m0, s18
	s_nop 0
	global_load_lds_dwordx4 v[214:215], off
	s_mov_b32 m0, s19
	s_nop 0
	global_load_lds_dwordx4 v[222:223], off
	s_waitcnt vmcnt(8)
	s_waitcnt lgkmcnt(0)
	s_barrier
; #define PG8_STAGE(bufoff, gbase, voff) do { _Pragma("unroll") for (int _i = 0; _i < 2; ++_i) \
;         __builtin_amdgcn_global_load_lds((const unsigned*)((const char*)(gbase) + (voff)[_i]), (PG8_LAS unsigned*)(lds + (bufoff) + ldsw + _i * 8192), 16, 0, 0); } while (0)
; #define PG8_LDA(dst, b, h) do { _Pragma("unroll") for (int m = 0; m < 4; ++m) _Pragma("unroll") for (int k = 0; k < 2; ++k) dst[m][k] = *(const PG8_LAS bf16x8*)(lds + PG8_SA(b, h) + aoff + m * 2048 + k * 1024); } while (0)
; #define PG8_LDB(dst, b, h) do { _Pragma("unroll") for (int n = 0; n < 2; ++n) _Pragma("unroll") for (int k = 0; k < 2; ++k) dst[n][k] = *(const PG8_LAS bf16x8*)(lds + PG8_SB(b, h) + boff + n * 2048 + k * 1024); } while (0)
; #define PG8_MMA(ai, bj, At, Bt) do { __builtin_amdgcn_s_setprio(1); _Pragma("unroll") for (int m = 0; m < 4; ++m) _Pragma("unroll") for (int n = 0; n < 2; ++n) _Pragma("unroll") for (int k = 0; k < 2; ++k) \
;         acc[ai][bj][m][n] = __builtin_amdgcn_mfma_f32_16x16x32_bf16(Bt[n][k], At[m][k], acc[ai][bj][m][n], 0, 0, 0); __builtin_amdgcn_s_setprio(0); } while (0)
; #define PG8_WAIT_V(n) asm volatile("s_waitcnt vmcnt(" #n ")" ::: "memory")
; #define PG8_WAIT_L(n) asm volatile("s_waitcnt lgkmcnt(" #n ")" ::: "memory")
; #define PG8_BAR __builtin_amdgcn_s_barrier()
; #define PG8_SCHED __builtin_amdgcn_sched_barrier(0)
; template <class Epi, class Sched, bool ALIGN_EPI = false, bool SP2 = false>
; __device__ __forceinline__ void gemm_phase(PG8_LAS unsigned char* lds, const Gemm g, const Sched& S, const Epi& E) {
;     ...
;             PG8_LDA(At, 0, 1); PG8_STAGE(PG8_SB(0, 0), b2, voffB); PG8_STAGE(PG8_SB(0, 1), b2 + hstep, voffB); PG8_STAGE(PG8_SA(0, 0), a2, voffA);
;             PG8_WAIT_V(8); PG8_WAIT_L(0); PG8_BAR; PG8_MMA(1, 0, At, B0); PG8_MMA(1, 1, At, B1); PG8_BAR; PG8_SCHED;
;             PG8_LDB(B0, 1, 0); PG8_LDB(B1, 1, 1); PG8_SCHED; PG8_LDA(At, 1, 0); PG8_STAGE(PG8_SA(0, 1), a2 + hstep, voffA);
;             PG8_WAIT_V(8); PG8_WAIT_L(0); PG8_BAR; PG8_MMA(0, 0, At, B0); PG8_MMA(0, 1, At, B1); PG8_BAR; PG8_SCHED;
	v_mfma_f32_16x16x32_bf16 v[60:63], v[140:143], v[176:179], v[60:63]
	v_mfma_f32_16x16x32_bf16 v[52:55], v[152:155], v[176:179], v[52:55]
	v_mfma_f32_16x16x32_bf16 v[44:47], v[140:143], v[184:187], v[44:47]
	v_mfma_f32_16x16x32_bf16 v[36:39], v[152:155], v[184:187], v[36:39]
	v_mfma_f32_16x16x32_bf16 v[28:31], v[140:143], v[192:195], v[28:31]
	v_mfma_f32_16x16x32_bf16 v[20:23], v[152:155], v[192:195], v[20:23]
	v_mfma_f32_16x16x32_bf16 v[12:15], v[140:143], v[200:203], v[12:15]
	v_mfma_f32_16x16x32_bf16 v[4:7], v[152:155], v[200:203], v[4:7]
	v_mfma_f32_16x16x32_bf16 v[60:63], v[148:151], v[180:183], v[60:63]
	v_mfma_f32_16x16x32_bf16 v[52:55], v[156:159], v[180:183], v[52:55]
	v_mfma_f32_16x16x32_bf16 v[44:47], v[148:151], v[188:191], v[44:47]
	v_mfma_f32_16x16x32_bf16 v[36:39], v[156:159], v[188:191], v[36:39]
	v_mfma_f32_16x16x32_bf16 v[28:31], v[148:151], v[196:199], v[28:31]
	v_mfma_f32_16x16x32_bf16 v[20:23], v[156:159], v[196:199], v[20:23]
	v_mfma_f32_16x16x32_bf16 v[12:15], v[148:151], v[204:207], v[12:15]
	v_mfma_f32_16x16x32_bf16 v[4:7], v[156:159], v[204:207], v[4:7]
	v_mfma_f32_16x16x32_bf16 v[56:59], v[160:163], v[176:179], v[56:59]
	v_mfma_f32_16x16x32_bf16 v[48:51], v[168:171], v[176:179], v[48:51]
	v_mfma_f32_16x16x32_bf16 v[40:43], v[160:163], v[184:187], v[40:43]
	v_mfma_f32_16x16x32_bf16 v[32:35], v[168:171], v[184:187], v[32:35]
	v_mfma_f32_16x16x32_bf16 v[24:27], v[160:163], v[192:195], v[24:27]
	v_mfma_f32_16x16x32_bf16 v[16:19], v[168:171], v[192:195], v[16:19]
	v_mfma_f32_16x16x32_bf16 v[8:11], v[160:163], v[200:203], v[8:11]
	v_mfma_f32_16x16x32_bf16 v[0:3], v[168:171], v[200:203], v[0:3]
	v_mfma_f32_16x16x32_bf16 v[56:59], v[164:167], v[180:183], v[56:59]
	v_mfma_f32_16x16x32_bf16 v[48:51], v[172:175], v[180:183], v[48:51]
	v_mfma_f32_16x16x32_bf16 v[40:43], v[164:167], v[188:191], v[40:43]
	v_mfma_f32_16x16x32_bf16 v[32:35], v[172:175], v[188:191], v[32:35]
	v_mfma_f32_16x16x32_bf16 v[24:27], v[164:167], v[196:199], v[24:27]
	v_mfma_f32_16x16x32_bf16 v[16:19], v[172:175], v[196:199], v[16:19]
	v_mfma_f32_16x16x32_bf16 v[8:11], v[164:167], v[204:207], v[8:11]
	v_mfma_f32_16x16x32_bf16 v[0:3], v[172:175], v[204:207], v[0:3]
	s_barrier
	s_add_i32 s8, 0, 0x18000
	s_add_i32 s37, 0, 0x1c000
	v_add_u32_e32 v156, s8, v145
	v_add_u32_e32 v172, s37, v145
	ds_read_b128 v[140:143], v156
	ds_read_b128 v[148:151], v156 offset:1024
	ds_read_b128 v[152:155], v156 offset:2048
	ds_read_b128 v[156:159], v156 offset:3072
	ds_read_b128 v[160:163], v172
	ds_read_b128 v[164:167], v172 offset:1024
	ds_read_b128 v[168:171], v172 offset:2048
	ds_read_b128 v[172:175], v172 offset:3072
	s_add_u32 s64, s64, 0x40000
	s_addc_u32 s65, s65, 0
	s_mov_b32 m0, s20
	v_lshl_add_u64 v[228:229], s[64:65], 0, v[134:135]
	ds_read_b128 v[176:179], v147 offset:32768
	ds_read_b128 v[180:183], v147 offset:33792
	ds_read_b128 v[184:187], v147 offset:34816
	ds_read_b128 v[188:191], v147 offset:35840
	ds_read_b128 v[192:195], v147 offset:36864
	ds_read_b128 v[196:199], v147 offset:37888
	ds_read_b128 v[200:203], v147 offset:38912
	ds_read_b128 v[204:207], v147 offset:39936
	global_load_lds_dwordx4 v[228:229], off
	v_lshl_add_u64 v[228:229], s[64:65], 0, v[132:133]
	s_mov_b32 m0, s21
	s_nop 0
	global_load_lds_dwordx4 v[228:229], off
	s_waitcnt vmcnt(8)
	s_waitcnt lgkmcnt(0)
	s_barrier
	v_mfma_f32_16x16x32_bf16 v[124:127], v[140:143], v[176:179], v[124:127]
	v_mfma_f32_16x16x32_bf16 v[116:119], v[152:155], v[176:179], v[116:119]
	v_mfma_f32_16x16x32_bf16 v[108:111], v[140:143], v[184:187], v[108:111]
	v_mfma_f32_16x16x32_bf16 v[100:103], v[152:155], v[184:187], v[100:103]
	v_mfma_f32_16x16x32_bf16 v[92:95], v[140:143], v[192:195], v[92:95]
	v_mfma_f32_16x16x32_bf16 v[84:87], v[152:155], v[192:195], v[84:87]
	v_mfma_f32_16x16x32_bf16 v[76:79], v[140:143], v[200:203], v[76:79]
	v_mfma_f32_16x16x32_bf16 v[68:71], v[152:155], v[200:203], v[68:71]
	v_mfma_f32_16x16x32_bf16 v[124:127], v[148:151], v[180:183], v[124:127]
	v_mfma_f32_16x16x32_bf16 v[116:119], v[156:159], v[180:183], v[116:119]
	v_mfma_f32_16x16x32_bf16 v[108:111], v[148:151], v[188:191], v[108:111]
	v_mfma_f32_16x16x32_bf16 v[100:103], v[156:159], v[188:191], v[100:103]
	v_mfma_f32_16x16x32_bf16 v[92:95], v[148:151], v[196:199], v[92:95]
	v_mfma_f32_16x16x32_bf16 v[84:87], v[156:159], v[196:199], v[84:87]
	v_mfma_f32_16x16x32_bf16 v[76:79], v[148:151], v[204:207], v[76:79]
	v_mfma_f32_16x16x32_bf16 v[68:71], v[156:159], v[204:207], v[68:71]
	v_mfma_f32_16x16x32_bf16 v[120:123], v[160:163], v[176:179], v[120:123]
	v_mfma_f32_16x16x32_bf16 v[112:115], v[168:171], v[176:179], v[112:115]
	v_mfma_f32_16x16x32_bf16 v[104:107], v[160:163], v[184:187], v[104:107]
	v_mfma_f32_16x16x32_bf16 v[96:99], v[168:171], v[184:187], v[96:99]
	v_mfma_f32_16x16x32_bf16 v[88:91], v[160:163], v[192:195], v[88:91]
	v_mfma_f32_16x16x32_bf16 v[80:83], v[168:171], v[192:195], v[80:83]
	v_mfma_f32_16x16x32_bf16 v[72:75], v[160:163], v[200:203], v[72:75]
	v_mfma_f32_16x16x32_bf16 v[64:67], v[168:171], v[200:203], v[64:67]
	v_mfma_f32_16x16x32_bf16 v[120:123], v[164:167], v[180:183], v[120:123]
	v_mfma_f32_16x16x32_bf16 v[112:115], v[172:175], v[180:183], v[112:115]
	v_mfma_f32_16x16x32_bf16 v[104:107], v[164:167], v[188:191], v[104:107]
	v_mfma_f32_16x16x32_bf16 v[96:99], v[172:175], v[188:191], v[96:99]
	v_mfma_f32_16x16x32_bf16 v[88:91], v[164:167], v[196:199], v[88:91]
	v_mfma_f32_16x16x32_bf16 v[80:83], v[172:175], v[196:199], v[80:83]
	v_mfma_f32_16x16x32_bf16 v[72:75], v[164:167], v[204:207], v[72:75]
	v_mfma_f32_16x16x32_bf16 v[64:67], v[172:175], v[204:207], v[64:67]
	s_barrier
; #define PG8_STAGE(bufoff, gbase, voff) do { _Pragma("unroll") for (int _i = 0; _i < 2; ++_i) \
;         __builtin_amdgcn_global_load_lds((const unsigned*)((const char*)(gbase) + (voff)[_i]), (PG8_LAS unsigned*)(lds + (bufoff) + ldsw + _i * 8192), 16, 0, 0); } while (0)
; #define PG8_LDA(dst, b, h) do { _Pragma("unroll") for (int m = 0; m < 4; ++m) _Pragma("unroll") for (int k = 0; k < 2; ++k) dst[m][k] = *(const PG8_LAS bf16x8*)(lds + PG8_SA(b, h) + aoff + m * 2048 + k * 1024); } while (0)
; #define PG8_MMA(ai, bj, At, Bt) do { __builtin_amdgcn_s_setprio(1); _Pragma("unroll") for (int m = 0; m < 4; ++m) _Pragma("unroll") for (int n = 0; n < 2; ++n) _Pragma("unroll") for (int k = 0; k < 2; ++k) \
;         acc[ai][bj][m][n] = __builtin_amdgcn_mfma_f32_16x16x32_bf16(Bt[n][k], At[m][k], acc[ai][bj][m][n], 0, 0, 0); __builtin_amdgcn_s_setprio(0); } while (0)
; #define PG8_WAIT_V(n) asm volatile("s_waitcnt vmcnt(" #n ")" ::: "memory")
; #define PG8_WAIT_L(n) asm volatile("s_waitcnt lgkmcnt(" #n ")" ::: "memory")
; #define PG8_BAR __builtin_amdgcn_s_barrier()
; #define PG8_SCHED __builtin_amdgcn_sched_barrier(0)
; template <class Epi, class Sched, bool ALIGN_EPI = false, bool SP2 = false>
; __device__ __forceinline__ void gemm_phase(PG8_LAS unsigned char* lds, const Gemm g, const Sched& S, const Epi& E) {
;     ...
;         for (int t = 0; t < nt; t += 2) {
;             const bool last = (t == nt - 2);
;             const char* a1 = cA + (size_t)(t + 1) * kstep;
;             const char* a2 = last ? nA : cA + (size_t)(t + 2) * kstep; const char* b2 = last ? nB : cB + (size_t)(t + 2) * kstep;
;             const char* a3 = a2 + kstep; const char* b3 = b2 + kstep;
;     ...
;             PG8_LDA(At, 1, 1); PG8_STAGE(PG8_SB(1, 0), b3, voffB); PG8_STAGE(PG8_SB(1, 1), b3 + hstep, voffB); PG8_STAGE(PG8_SA(1, 0), a3, voffA);
;             PG8_WAIT_V(8); PG8_WAIT_L(0); PG8_BAR; PG8_MMA(1, 0, At, B0); PG8_MMA(1, 1, At, B1); PG8_BAR; PG8_SCHED;
	s_add_i32 s8, s8, s17
	v_lshl_add_u64 v[208:209], v[208:209], 0, s[90:91]
	s_mov_b32 m0, s8
	ds_read_b128 v[176:179], v147 offset:49152
	ds_read_b128 v[180:183], v147 offset:50176
	ds_read_b128 v[184:187], v147 offset:51200
	ds_read_b128 v[188:191], v147 offset:52224
	ds_read_b128 v[192:195], v147 offset:53248
	ds_read_b128 v[196:199], v147 offset:54272
	ds_read_b128 v[200:203], v147 offset:55296
	ds_read_b128 v[204:207], v147 offset:56320
	global_load_lds_dwordx4 v[208:209], off
	s_add_i32 m0, s8, 0x2000
	s_add_u32 s58, s58, 0x40080
	v_lshl_add_u64 v[208:209], v[210:211], 0, s[90:91]
	s_addc_u32 s59, s59, 0
	s_add_i32 s8, s37, s17
	global_load_lds_dwordx4 v[208:209], off
	v_lshl_add_u64 v[208:209], s[58:59], 0, v[128:129]
	s_mov_b32 m0, s8
	s_nop 0
	global_load_lds_dwordx4 v[208:209], off
	v_lshl_add_u64 v[208:209], s[58:59], 0, v[130:131]
	s_add_i32 m0, s8, 0x2000
	s_nop 0
	global_load_lds_dwordx4 v[208:209], off
	v_lshl_add_u64 v[208:209], v[214:215], 0, s[90:91]
	s_mov_b32 m0, s22
	s_nop 0
	global_load_lds_dwordx4 v[208:209], off
	v_lshl_add_u64 v[208:209], v[222:223], 0, s[90:91]
	s_mov_b32 m0, s23
	s_nop 0
	global_load_lds_dwordx4 v[208:209], off
	s_waitcnt vmcnt(8)
	s_waitcnt lgkmcnt(0)
	s_barrier
	v_mfma_f32_16x16x32_bf16 v[60:63], v[140:143], v[176:179], v[60:63]
	v_mfma_f32_16x16x32_bf16 v[52:55], v[152:155], v[176:179], v[52:55]
	v_mfma_f32_16x16x32_bf16 v[44:47], v[140:143], v[184:187], v[44:47]
	v_mfma_f32_16x16x32_bf16 v[36:39], v[152:155], v[184:187], v[36:39]
	v_mfma_f32_16x16x32_bf16 v[28:31], v[140:143], v[192:195], v[28:31]
	v_mfma_f32_16x16x32_bf16 v[20:23], v[152:155], v[192:195], v[20:23]
	v_mfma_f32_16x16x32_bf16 v[12:15], v[140:143], v[200:203], v[12:15]
	v_mfma_f32_16x16x32_bf16 v[4:7], v[152:155], v[200:203], v[4:7]
	v_mfma_f32_16x16x32_bf16 v[60:63], v[148:151], v[180:183], v[60:63]
	v_mfma_f32_16x16x32_bf16 v[52:55], v[156:159], v[180:183], v[52:55]
	v_mfma_f32_16x16x32_bf16 v[44:47], v[148:151], v[188:191], v[44:47]
	v_mfma_f32_16x16x32_bf16 v[36:39], v[156:159], v[188:191], v[36:39]
	v_mfma_f32_16x16x32_bf16 v[28:31], v[148:151], v[196:199], v[28:31]
	v_mfma_f32_16x16x32_bf16 v[20:23], v[156:159], v[196:199], v[20:23]
	v_mfma_f32_16x16x32_bf16 v[12:15], v[148:151], v[204:207], v[12:15]
	v_mfma_f32_16x16x32_bf16 v[4:7], v[156:159], v[204:207], v[4:7]
	v_mfma_f32_16x16x32_bf16 v[56:59], v[160:163], v[176:179], v[56:59]
	v_mfma_f32_16x16x32_bf16 v[48:51], v[168:171], v[176:179], v[48:51]
	v_mfma_f32_16x16x32_bf16 v[40:43], v[160:163], v[184:187], v[40:43]
	v_mfma_f32_16x16x32_bf16 v[32:35], v[168:171], v[184:187], v[32:35]
	v_mfma_f32_16x16x32_bf16 v[24:27], v[160:163], v[192:195], v[24:27]
	v_mfma_f32_16x16x32_bf16 v[16:19], v[168:171], v[192:195], v[16:19]
	v_mfma_f32_16x16x32_bf16 v[8:11], v[160:163], v[200:203], v[8:11]
	v_mfma_f32_16x16x32_bf16 v[0:3], v[168:171], v[200:203], v[0:3]
	v_mfma_f32_16x16x32_bf16 v[56:59], v[164:167], v[180:183], v[56:59]
	v_mfma_f32_16x16x32_bf16 v[48:51], v[172:175], v[180:183], v[48:51]
	v_mfma_f32_16x16x32_bf16 v[40:43], v[164:167], v[188:191], v[40:43]
	v_mfma_f32_16x16x32_bf16 v[32:35], v[172:175], v[188:191], v[32:35]
	v_mfma_f32_16x16x32_bf16 v[24:27], v[164:167], v[196:199], v[24:27]
	v_mfma_f32_16x16x32_bf16 v[16:19], v[172:175], v[196:199], v[16:19]
	v_mfma_f32_16x16x32_bf16 v[8:11], v[164:167], v[204:207], v[8:11]
	v_mfma_f32_16x16x32_bf16 v[0:3], v[172:175], v[204:207], v[0:3]
	s_barrier
	s_add_i32 s36, s36, 2
	s_add_u32 s66, s66, 0x100
	s_addc_u32 s67, s67, 0
	s_add_u32 s34, s34, 0x100
	s_addc_u32 s35, s35, 0
	s_cmp_gt_u32 s36, 13
	s_cbranch_scc0 .LBB0_813
	s_setprio 0
	s_and_b64 vcc, exec, s[46:47]
	s_cbranch_vccz .LBB0_816
	s_barrier

; #define PG8_STAGE(bufoff, gbase, voff) do { _Pragma("unroll") for (int _i = 0; _i < 2; ++_i) \
;         __builtin_amdgcn_global_load_lds((const unsigned*)((const char*)(gbase) + (voff)[_i]), (PG8_LAS unsigned*)(lds + (bufoff) + ldsw + _i * 8192), 16, 0, 0); } while (0)
; #define PG8_LDA(dst, b, h) do { _Pragma("unroll") for (int m = 0; m < 4; ++m) _Pragma("unroll") for (int k = 0; k < 2; ++k) dst[m][k] = *(const PG8_LAS bf16x8*)(lds + PG8_SA(b, h) + aoff + m * 2048 + k * 1024); } while (0)
; #define PG8_LDB(dst, b, h) do { _Pragma("unroll") for (int n = 0; n < 2; ++n) _Pragma("unroll") for (int k = 0; k < 2; ++k) dst[n][k] = *(const PG8_LAS bf16x8*)(lds + PG8_SB(b, h) + boff + n * 2048 + k * 1024); } while (0)
; #define PG8_WAIT_V(n) asm volatile("s_waitcnt vmcnt(" #n ")" ::: "memory")
; #define PG8_WAIT_L(n) asm volatile("s_waitcnt lgkmcnt(" #n ")" ::: "memory")
; #define PG8_BAR __builtin_amdgcn_s_barrier()
; #define PG8_SCHED __builtin_amdgcn_sched_barrier(0)
; template <class Epi, class Sched, bool ALIGN_EPI = false, bool SP2 = false>
; __device__ __forceinline__ void gemm_phase(PG8_LAS unsigned char* lds, const Gemm g, const Sched& S, const Epi& E) {
;     ...
;         const bool has_next = S.next(ui + 1, nxt);
;         const char* nA = has_next ? (const char*)g.A + (size_t)nxt.pm * tstep : cA; const char* nB = has_next ? (const char*)g.Bt + (size_t)nxt.pn * tstep : cB;
;         for (int t = 0; t < nt; t += 2) {
;             const bool last = (t == nt - 2);
;             const char* a1 = cA + (size_t)(t + 1) * kstep;
;             const char* a2 = last ? nA : cA + (size_t)(t + 2) * kstep; const char* b2 = last ? nB : cB + (size_t)(t + 2) * kstep;
;             const char* a3 = a2 + kstep; const char* b3 = b2 + kstep;
;             if (last && has_next) S.a_ready(nxt);
;             if constexpr (SP2) {
;             PG8_LDB(B0, 0, 0); PG8_LDB(B1, 0, 1); PG8_SCHED; PG8_LDA(At, 0, 0); PG8_STAGE(PG8_SA(1, 1), a1 + hstep, voffA);
;             PG8_WAIT_V(8); PG8_WAIT_L(0); PG8_BAR; PG8_MMA(0, 0, At, B0); PG8_MMA(0, 1, At, B1); PG8_BAR; PG8_SCHED;
;             PG8_LDA(At, 0, 1); PG8_STAGE(PG8_SB(0, 0), b2, voffB); PG8_STAGE(PG8_SB(0, 1), b2 + hstep, voffB); PG8_STAGE(PG8_SA(0, 0), a2, voffA);
;             PG8_WAIT_V(8); PG8_WAIT_L(0); PG8_BAR; PG8_MMA(1, 0, At, B0); PG8_MMA(1, 1, At, B1); PG8_BAR; PG8_SCHED;
.Lsp_4:
.LBB0_957:
	s_add_u32 s44, s96, 0x100
	s_addc_u32 s45, s97, 0
	s_add_i32 s8, 0, 0x10000
	s_cmp_eq_u32 s70, 40
	s_cselect_b32 s65, s67, s45
	s_cselect_b32 s64, s66, s44
	s_cselect_b32 s47, s73, s37
	s_cselect_b32 s46, s72, s36
	s_add_i32 s88, 0, 0x14000
	v_add_u32_e32 v142, s8, v185
	v_add_u32_e32 v168, s88, v185
	ds_read_b128 v[130:133], v142
	ds_read_b128 v[134:137], v142 offset:1024
	ds_read_b128 v[138:141], v142 offset:2048
	ds_read_b128 v[142:145], v142 offset:3072
	ds_read_b128 v[156:159], v168
	ds_read_b128 v[160:163], v168 offset:1024
	ds_read_b128 v[164:167], v168 offset:2048
	ds_read_b128 v[168:171], v168 offset:3072
	v_lshl_add_u64 v[208:209], s[96:97], 0, v[152:153]
	s_add_i32 m0, s15, 0xc000
	ds_read_b128 v[172:175], v191
	ds_read_b128 v[176:179], v191 offset:1024
	ds_read_b128 v[180:183], v191 offset:2048
	ds_read_b128 v[186:189], v191 offset:3072
	ds_read_b128 v[192:195], v191 offset:4096
	ds_read_b128 v[196:199], v191 offset:5120
	ds_read_b128 v[200:203], v191 offset:6144
	ds_read_b128 v[204:207], v191 offset:7168
	global_load_lds_dwordx4 v[208:209], off
	v_lshl_add_u64 v[208:209], s[96:97], 0, v[154:155]
	s_add_i32 m0, s15, 0xe000
	s_nop 0
	global_load_lds_dwordx4 v[208:209], off
	s_waitcnt vmcnt(8)
	s_waitcnt lgkmcnt(0)
	s_barrier
	v_mfma_f32_16x16x32_bf16 v[124:127], v[130:133], v[172:175], v[124:127]
	v_mfma_f32_16x16x32_bf16 v[120:123], v[138:141], v[172:175], v[120:123]
	v_mfma_f32_16x16x32_bf16 v[108:111], v[130:133], v[180:183], v[108:111]
	v_mfma_f32_16x16x32_bf16 v[104:107], v[138:141], v[180:183], v[104:107]
	v_mfma_f32_16x16x32_bf16 v[92:95], v[130:133], v[192:195], v[92:95]
	v_mfma_f32_16x16x32_bf16 v[88:91], v[138:141], v[192:195], v[88:91]
	v_mfma_f32_16x16x32_bf16 v[76:79], v[130:133], v[200:203], v[76:79]
	v_mfma_f32_16x16x32_bf16 v[72:75], v[138:141], v[200:203], v[72:75]
	v_mfma_f32_16x16x32_bf16 v[124:127], v[134:137], v[176:179], v[124:127]
	v_mfma_f32_16x16x32_bf16 v[120:123], v[142:145], v[176:179], v[120:123]
	v_mfma_f32_16x16x32_bf16 v[108:111], v[134:137], v[186:189], v[108:111]
	v_mfma_f32_16x16x32_bf16 v[104:107], v[142:145], v[186:189], v[104:107]
	v_mfma_f32_16x16x32_bf16 v[92:95], v[134:137], v[196:199], v[92:95]
	v_mfma_f32_16x16x32_bf16 v[88:91], v[142:145], v[196:199], v[88:91]
	v_mfma_f32_16x16x32_bf16 v[76:79], v[134:137], v[204:207], v[76:79]
	v_mfma_f32_16x16x32_bf16 v[72:75], v[142:145], v[204:207], v[72:75]
	v_mfma_f32_16x16x32_bf16 v[116:119], v[156:159], v[172:175], v[116:119]
	v_mfma_f32_16x16x32_bf16 v[112:115], v[164:167], v[172:175], v[112:115]
	v_mfma_f32_16x16x32_bf16 v[100:103], v[156:159], v[180:183], v[100:103]
	v_mfma_f32_16x16x32_bf16 v[96:99], v[164:167], v[180:183], v[96:99]
	v_mfma_f32_16x16x32_bf16 v[84:87], v[156:159], v[192:195], v[84:87]
	v_mfma_f32_16x16x32_bf16 v[80:83], v[164:167], v[192:195], v[80:83]
	v_mfma_f32_16x16x32_bf16 v[68:71], v[156:159], v[200:203], v[68:71]
	v_mfma_f32_16x16x32_bf16 v[64:67], v[164:167], v[200:203], v[64:67]
	v_mfma_f32_16x16x32_bf16 v[116:119], v[160:163], v[176:179], v[116:119]
	v_mfma_f32_16x16x32_bf16 v[112:115], v[168:171], v[176:179], v[112:115]
	v_mfma_f32_16x16x32_bf16 v[100:103], v[160:163], v[186:189], v[100:103]
	v_mfma_f32_16x16x32_bf16 v[96:99], v[168:171], v[186:189], v[96:99]
	v_mfma_f32_16x16x32_bf16 v[84:87], v[160:163], v[196:199], v[84:87]
	v_mfma_f32_16x16x32_bf16 v[80:83], v[168:171], v[196:199], v[80:83]
	v_mfma_f32_16x16x32_bf16 v[68:71], v[160:163], v[204:207], v[68:71]
	v_mfma_f32_16x16x32_bf16 v[64:67], v[168:171], v[204:207], v[64:67]
	s_barrier
	s_add_i32 s8, s8, s14
	v_lshl_add_u64 v[208:209], s[46:47], 0, v[128:129]
	s_mov_b32 m0, s8
	ds_read_b128 v[172:175], v191 offset:16384
	ds_read_b128 v[176:179], v191 offset:17408
	ds_read_b128 v[180:183], v191 offset:18432
	ds_read_b128 v[186:189], v191 offset:19456
	ds_read_b128 v[192:195], v191 offset:20480
	ds_read_b128 v[196:199], v191 offset:21504
	ds_read_b128 v[200:203], v191 offset:22528
	ds_read_b128 v[204:207], v191 offset:23552
	global_load_lds_dwordx4 v[208:209], off
	s_add_i32 m0, s8, 0x2000
	s_add_u32 s84, s46, 0xb0000
	v_lshl_add_u64 v[210:211], s[46:47], 0, v[146:147]
	s_addc_u32 s85, s47, 0
	s_add_i32 s8, s88, s14
	global_load_lds_dwordx4 v[210:211], off
	v_lshl_add_u64 v[214:215], s[84:85], 0, v[128:129]
	s_mov_b32 m0, s8
	v_lshl_add_u64 v[222:223], s[64:65], 0, v[148:149]
	global_load_lds_dwordx4 v[214:215], off
	v_lshl_add_u64 v[214:215], s[84:85], 0, v[146:147]
	s_add_i32 m0, s8, 0x2000
	s_nop 0
	global_load_lds_dwordx4 v[214:215], off
	v_lshl_add_u64 v[214:215], s[64:65], 0, v[150:151]
	s_mov_b32 m0, s15
	s_nop 0
	global_load_lds_dwordx4 v[214:215], off
	s_mov_b32 m0, s18
	s_nop 0
	global_load_lds_dwordx4 v[222:223], off
	s_waitcnt vmcnt(8)
	s_waitcnt lgkmcnt(0)
	s_barrier
; #define PG8_STAGE(bufoff, gbase, voff) do { _Pragma("unroll") for (int _i = 0; _i < 2; ++_i) \
;         __builtin_amdgcn_global_load_lds((const unsigned*)((const char*)(gbase) + (voff)[_i]), (PG8_LAS unsigned*)(lds + (bufoff) + ldsw + _i * 8192), 16, 0, 0); } while (0)
; #define PG8_LDA(dst, b, h) do { _Pragma("unroll") for (int m = 0; m < 4; ++m) _Pragma("unroll") for (int k = 0; k < 2; ++k) dst[m][k] = *(const PG8_LAS bf16x8*)(lds + PG8_SA(b, h) + aoff + m * 2048 + k * 1024); } while (0)
; #define PG8_LDB(dst, b, h) do { _Pragma("unroll") for (int n = 0; n < 2; ++n) _Pragma("unroll") for (int k = 0; k < 2; ++k) dst[n][k] = *(const PG8_LAS bf16x8*)(lds + PG8_SB(b, h) + boff + n * 2048 + k * 1024); } while (0)
; #define PG8_MMA(ai, bj, At, Bt) do { __builtin_amdgcn_s_setprio(1); _Pragma("unroll") for (int m = 0; m < 4; ++m) _Pragma("unroll") for (int n = 0; n < 2; ++n) _Pragma("unroll") for (int k = 0; k < 2; ++k) \
;         acc[ai][bj][m][n] = __builtin_amdgcn_mfma_f32_16x16x32_bf16(Bt[n][k], At[m][k], acc[ai][bj][m][n], 0, 0, 0); __builtin_amdgcn_s_setprio(0); } while (0)
; #define PG8_WAIT_V(n) asm volatile("s_waitcnt vmcnt(" #n ")" ::: "memory")
; #define PG8_WAIT_L(n) asm volatile("s_waitcnt lgkmcnt(" #n ")" ::: "memory")
; #define PG8_BAR __builtin_amdgcn_s_barrier()
; #define PG8_SCHED __builtin_amdgcn_sched_barrier(0)
; template <class Epi, class Sched, bool ALIGN_EPI = false, bool SP2 = false>
; __device__ __forceinline__ void gemm_phase(PG8_LAS unsigned char* lds, const Gemm g, const Sched& S, const Epi& E) {
;     ...
;             PG8_LDA(At, 0, 1); PG8_STAGE(PG8_SB(0, 0), b2, voffB); PG8_STAGE(PG8_SB(0, 1), b2 + hstep, voffB); PG8_STAGE(PG8_SA(0, 0), a2, voffA);
;             PG8_WAIT_V(8); PG8_WAIT_L(0); PG8_BAR; PG8_MMA(1, 0, At, B0); PG8_MMA(1, 1, At, B1); PG8_BAR; PG8_SCHED;
;             PG8_LDB(B0, 1, 0); PG8_LDB(B1, 1, 1); PG8_SCHED; PG8_LDA(At, 1, 0); PG8_STAGE(PG8_SA(0, 1), a2 + hstep, voffA);
;             PG8_WAIT_V(8); PG8_WAIT_L(0); PG8_BAR; PG8_MMA(0, 0, At, B0); PG8_MMA(0, 1, At, B1); PG8_BAR; PG8_SCHED;
	v_mfma_f32_16x16x32_bf16 v[60:63], v[130:133], v[172:175], v[60:63]
	v_mfma_f32_16x16x32_bf16 v[56:59], v[138:141], v[172:175], v[56:59]
	v_mfma_f32_16x16x32_bf16 v[44:47], v[130:133], v[180:183], v[44:47]
	v_mfma_f32_16x16x32_bf16 v[40:43], v[138:141], v[180:183], v[40:43]
	v_mfma_f32_16x16x32_bf16 v[28:31], v[130:133], v[192:195], v[28:31]
	v_mfma_f32_16x16x32_bf16 v[24:27], v[138:141], v[192:195], v[24:27]
	v_mfma_f32_16x16x32_bf16 v[12:15], v[130:133], v[200:203], v[12:15]
	v_mfma_f32_16x16x32_bf16 v[8:11], v[138:141], v[200:203], v[8:11]
	v_mfma_f32_16x16x32_bf16 v[60:63], v[134:137], v[176:179], v[60:63]
	v_mfma_f32_16x16x32_bf16 v[56:59], v[142:145], v[176:179], v[56:59]
	v_mfma_f32_16x16x32_bf16 v[44:47], v[134:137], v[186:189], v[44:47]
	v_mfma_f32_16x16x32_bf16 v[40:43], v[142:145], v[186:189], v[40:43]
	v_mfma_f32_16x16x32_bf16 v[28:31], v[134:137], v[196:199], v[28:31]
	v_mfma_f32_16x16x32_bf16 v[24:27], v[142:145], v[196:199], v[24:27]
	v_mfma_f32_16x16x32_bf16 v[12:15], v[134:137], v[204:207], v[12:15]
	v_mfma_f32_16x16x32_bf16 v[8:11], v[142:145], v[204:207], v[8:11]
	v_mfma_f32_16x16x32_bf16 v[52:55], v[156:159], v[172:175], v[52:55]
	v_mfma_f32_16x16x32_bf16 v[48:51], v[164:167], v[172:175], v[48:51]
	v_mfma_f32_16x16x32_bf16 v[36:39], v[156:159], v[180:183], v[36:39]
	v_mfma_f32_16x16x32_bf16 v[32:35], v[164:167], v[180:183], v[32:35]
	v_mfma_f32_16x16x32_bf16 v[20:23], v[156:159], v[192:195], v[20:23]
	v_mfma_f32_16x16x32_bf16 v[16:19], v[164:167], v[192:195], v[16:19]
	v_mfma_f32_16x16x32_bf16 v[4:7], v[156:159], v[200:203], v[4:7]
	v_mfma_f32_16x16x32_bf16 v[0:3], v[164:167], v[200:203], v[0:3]
	v_mfma_f32_16x16x32_bf16 v[52:55], v[160:163], v[176:179], v[52:55]
	v_mfma_f32_16x16x32_bf16 v[48:51], v[168:171], v[176:179], v[48:51]
	v_mfma_f32_16x16x32_bf16 v[36:39], v[160:163], v[186:189], v[36:39]
	v_mfma_f32_16x16x32_bf16 v[32:35], v[168:171], v[186:189], v[32:35]
	v_mfma_f32_16x16x32_bf16 v[20:23], v[160:163], v[196:199], v[20:23]
	v_mfma_f32_16x16x32_bf16 v[16:19], v[168:171], v[196:199], v[16:19]
	v_mfma_f32_16x16x32_bf16 v[4:7], v[160:163], v[204:207], v[4:7]
	v_mfma_f32_16x16x32_bf16 v[0:3], v[168:171], v[204:207], v[0:3]
	s_barrier
	s_add_i32 s8, 0, 0x18000
	s_add_i32 s84, 0, 0x1c000
	v_add_u32_e32 v142, s8, v185
	v_add_u32_e32 v168, s84, v185
	ds_read_b128 v[130:133], v142
	ds_read_b128 v[134:137], v142 offset:1024
	ds_read_b128 v[138:141], v142 offset:2048
	ds_read_b128 v[142:145], v142 offset:3072
	ds_read_b128 v[156:159], v168
	ds_read_b128 v[160:163], v168 offset:1024
	ds_read_b128 v[164:167], v168 offset:2048
	ds_read_b128 v[168:171], v168 offset:3072
	s_add_u32 s64, s64, 0xb0000
	s_addc_u32 s65, s65, 0
	s_mov_b32 m0, s19
	v_lshl_add_u64 v[228:229], s[64:65], 0, v[150:151]
	ds_read_b128 v[172:175], v191 offset:32768
	ds_read_b128 v[176:179], v191 offset:33792
	ds_read_b128 v[180:183], v191 offset:34816
	ds_read_b128 v[186:189], v191 offset:35840
	ds_read_b128 v[192:195], v191 offset:36864
	ds_read_b128 v[196:199], v191 offset:37888
	ds_read_b128 v[200:203], v191 offset:38912
	ds_read_b128 v[204:207], v191 offset:39936
	global_load_lds_dwordx4 v[228:229], off
	v_lshl_add_u64 v[228:229], s[64:65], 0, v[148:149]
	s_mov_b32 m0, s20
	s_nop 0
	global_load_lds_dwordx4 v[228:229], off
	s_waitcnt vmcnt(8)
	s_waitcnt lgkmcnt(0)
	s_barrier
	v_mfma_f32_16x16x32_bf16 v[124:127], v[130:133], v[172:175], v[124:127]
	v_mfma_f32_16x16x32_bf16 v[120:123], v[138:141], v[172:175], v[120:123]
	v_mfma_f32_16x16x32_bf16 v[108:111], v[130:133], v[180:183], v[108:111]
	v_mfma_f32_16x16x32_bf16 v[104:107], v[138:141], v[180:183], v[104:107]
	v_mfma_f32_16x16x32_bf16 v[92:95], v[130:133], v[192:195], v[92:95]
	v_mfma_f32_16x16x32_bf16 v[88:91], v[138:141], v[192:195], v[88:91]
	v_mfma_f32_16x16x32_bf16 v[76:79], v[130:133], v[200:203], v[76:79]
	v_mfma_f32_16x16x32_bf16 v[72:75], v[138:141], v[200:203], v[72:75]
	v_mfma_f32_16x16x32_bf16 v[124:127], v[134:137], v[176:179], v[124:127]
	v_mfma_f32_16x16x32_bf16 v[120:123], v[142:145], v[176:179], v[120:123]
	v_mfma_f32_16x16x32_bf16 v[108:111], v[134:137], v[186:189], v[108:111]
	v_mfma_f32_16x16x32_bf16 v[104:107], v[142:145], v[186:189], v[104:107]
	v_mfma_f32_16x16x32_bf16 v[92:95], v[134:137], v[196:199], v[92:95]
	v_mfma_f32_16x16x32_bf16 v[88:91], v[142:145], v[196:199], v[88:91]
	v_mfma_f32_16x16x32_bf16 v[76:79], v[134:137], v[204:207], v[76:79]
	v_mfma_f32_16x16x32_bf16 v[72:75], v[142:145], v[204:207], v[72:75]
	v_mfma_f32_16x16x32_bf16 v[116:119], v[156:159], v[172:175], v[116:119]
	v_mfma_f32_16x16x32_bf16 v[112:115], v[164:167], v[172:175], v[112:115]
	v_mfma_f32_16x16x32_bf16 v[100:103], v[156:159], v[180:183], v[100:103]
	v_mfma_f32_16x16x32_bf16 v[96:99], v[164:167], v[180:183], v[96:99]
	v_mfma_f32_16x16x32_bf16 v[84:87], v[156:159], v[192:195], v[84:87]
	v_mfma_f32_16x16x32_bf16 v[80:83], v[164:167], v[192:195], v[80:83]
	v_mfma_f32_16x16x32_bf16 v[68:71], v[156:159], v[200:203], v[68:71]
	v_mfma_f32_16x16x32_bf16 v[64:67], v[164:167], v[200:203], v[64:67]
	v_mfma_f32_16x16x32_bf16 v[116:119], v[160:163], v[176:179], v[116:119]
	v_mfma_f32_16x16x32_bf16 v[112:115], v[168:171], v[176:179], v[112:115]
	v_mfma_f32_16x16x32_bf16 v[100:103], v[160:163], v[186:189], v[100:103]
	v_mfma_f32_16x16x32_bf16 v[96:99], v[168:171], v[186:189], v[96:99]
	v_mfma_f32_16x16x32_bf16 v[84:87], v[160:163], v[196:199], v[84:87]
	v_mfma_f32_16x16x32_bf16 v[80:83], v[168:171], v[196:199], v[80:83]
	v_mfma_f32_16x16x32_bf16 v[68:71], v[160:163], v[204:207], v[68:71]
	v_mfma_f32_16x16x32_bf16 v[64:67], v[168:171], v[204:207], v[64:67]
	s_barrier
; #define PG8_STAGE(bufoff, gbase, voff) do { _Pragma("unroll") for (int _i = 0; _i < 2; ++_i) \
;         __builtin_amdgcn_global_load_lds((const unsigned*)((const char*)(gbase) + (voff)[_i]), (PG8_LAS unsigned*)(lds + (bufoff) + ldsw + _i * 8192), 16, 0, 0); } while (0)
; #define PG8_LDA(dst, b, h) do { _Pragma("unroll") for (int m = 0; m < 4; ++m) _Pragma("unroll") for (int k = 0; k < 2; ++k) dst[m][k] = *(const PG8_LAS bf16x8*)(lds + PG8_SA(b, h) + aoff + m * 2048 + k * 1024); } while (0)
; #define PG8_MMA(ai, bj, At, Bt) do { __builtin_amdgcn_s_setprio(1); _Pragma("unroll") for (int m = 0; m < 4; ++m) _Pragma("unroll") for (int n = 0; n < 2; ++n) _Pragma("unroll") for (int k = 0; k < 2; ++k) \
;         acc[ai][bj][m][n] = __builtin_amdgcn_mfma_f32_16x16x32_bf16(Bt[n][k], At[m][k], acc[ai][bj][m][n], 0, 0, 0); __builtin_amdgcn_s_setprio(0); } while (0)
; #define PG8_WAIT_V(n) asm volatile("s_waitcnt vmcnt(" #n ")" ::: "memory")
; #define PG8_WAIT_L(n) asm volatile("s_waitcnt lgkmcnt(" #n ")" ::: "memory")
; #define PG8_BAR __builtin_amdgcn_s_barrier()
; #define PG8_SCHED __builtin_amdgcn_sched_barrier(0)
; template <class Epi, class Sched, bool ALIGN_EPI = false, bool SP2 = false>
; __device__ __forceinline__ void gemm_phase(PG8_LAS unsigned char* lds, const Gemm g, const Sched& S, const Epi& E) {
;     ...
;         for (int t = 0; t < nt; t += 2) {
;             const bool last = (t == nt - 2);
;             const char* a1 = cA + (size_t)(t + 1) * kstep;
;             const char* a2 = last ? nA : cA + (size_t)(t + 2) * kstep; const char* b2 = last ? nB : cB + (size_t)(t + 2) * kstep;
;             const char* a3 = a2 + kstep; const char* b3 = b2 + kstep;
;     ...
;             PG8_LDA(At, 1, 1); PG8_STAGE(PG8_SB(1, 0), b3, voffB); PG8_STAGE(PG8_SB(1, 1), b3 + hstep, voffB); PG8_STAGE(PG8_SA(1, 0), a3, voffA);
;             PG8_WAIT_V(8); PG8_WAIT_L(0); PG8_BAR; PG8_MMA(1, 0, At, B0); PG8_MMA(1, 1, At, B1); PG8_BAR; PG8_SCHED;
	s_add_i32 s8, s8, s14
	v_lshl_add_u64 v[208:209], v[208:209], 0, s[90:91]
	s_mov_b32 m0, s8
	ds_read_b128 v[172:175], v191 offset:49152
	ds_read_b128 v[176:179], v191 offset:50176
	ds_read_b128 v[180:183], v191 offset:51200
	ds_read_b128 v[186:189], v191 offset:52224
	ds_read_b128 v[192:195], v191 offset:53248
	ds_read_b128 v[196:199], v191 offset:54272
	ds_read_b128 v[200:203], v191 offset:55296
	ds_read_b128 v[204:207], v191 offset:56320
	global_load_lds_dwordx4 v[208:209], off
	s_add_i32 m0, s8, 0x2000
	s_add_u32 s46, s46, 0xb0080
	v_lshl_add_u64 v[208:209], v[210:211], 0, s[90:91]
	s_addc_u32 s47, s47, 0
	s_add_i32 s8, s84, s14
	global_load_lds_dwordx4 v[208:209], off
	v_lshl_add_u64 v[208:209], s[46:47], 0, v[128:129]
	s_mov_b32 m0, s8
	s_nop 0
	global_load_lds_dwordx4 v[208:209], off
	v_lshl_add_u64 v[208:209], s[46:47], 0, v[146:147]
	s_add_i32 m0, s8, 0x2000
	s_nop 0
	global_load_lds_dwordx4 v[208:209], off
	v_lshl_add_u64 v[208:209], v[214:215], 0, s[90:91]
	s_mov_b32 m0, s27
	s_nop 0
	global_load_lds_dwordx4 v[208:209], off
	v_lshl_add_u64 v[208:209], v[222:223], 0, s[90:91]
	s_mov_b32 m0, s28
	s_nop 0
	global_load_lds_dwordx4 v[208:209], off
	s_waitcnt vmcnt(8)
	s_waitcnt lgkmcnt(0)
	s_barrier
	v_mfma_f32_16x16x32_bf16 v[60:63], v[130:133], v[172:175], v[60:63]
	v_mfma_f32_16x16x32_bf16 v[56:59], v[138:141], v[172:175], v[56:59]
	v_mfma_f32_16x16x32_bf16 v[44:47], v[130:133], v[180:183], v[44:47]
	v_mfma_f32_16x16x32_bf16 v[40:43], v[138:141], v[180:183], v[40:43]
	v_mfma_f32_16x16x32_bf16 v[28:31], v[130:133], v[192:195], v[28:31]
	v_mfma_f32_16x16x32_bf16 v[24:27], v[138:141], v[192:195], v[24:27]
	v_mfma_f32_16x16x32_bf16 v[12:15], v[130:133], v[200:203], v[12:15]
	v_mfma_f32_16x16x32_bf16 v[8:11], v[138:141], v[200:203], v[8:11]
	v_mfma_f32_16x16x32_bf16 v[60:63], v[134:137], v[176:179], v[60:63]
	v_mfma_f32_16x16x32_bf16 v[56:59], v[142:145], v[176:179], v[56:59]
	v_mfma_f32_16x16x32_bf16 v[44:47], v[134:137], v[186:189], v[44:47]
	v_mfma_f32_16x16x32_bf16 v[40:43], v[142:145], v[186:189], v[40:43]
	v_mfma_f32_16x16x32_bf16 v[28:31], v[134:137], v[196:199], v[28:31]
	v_mfma_f32_16x16x32_bf16 v[24:27], v[142:145], v[196:199], v[24:27]
	v_mfma_f32_16x16x32_bf16 v[12:15], v[134:137], v[204:207], v[12:15]
	v_mfma_f32_16x16x32_bf16 v[8:11], v[142:145], v[204:207], v[8:11]
	v_mfma_f32_16x16x32_bf16 v[52:55], v[156:159], v[172:175], v[52:55]
	v_mfma_f32_16x16x32_bf16 v[48:51], v[164:167], v[172:175], v[48:51]
	v_mfma_f32_16x16x32_bf16 v[36:39], v[156:159], v[180:183], v[36:39]
	v_mfma_f32_16x16x32_bf16 v[32:35], v[164:167], v[180:183], v[32:35]
	v_mfma_f32_16x16x32_bf16 v[20:23], v[156:159], v[192:195], v[20:23]
	v_mfma_f32_16x16x32_bf16 v[16:19], v[164:167], v[192:195], v[16:19]
	v_mfma_f32_16x16x32_bf16 v[4:7], v[156:159], v[200:203], v[4:7]
	v_mfma_f32_16x16x32_bf16 v[0:3], v[164:167], v[200:203], v[0:3]
	v_mfma_f32_16x16x32_bf16 v[52:55], v[160:163], v[176:179], v[52:55]
	v_mfma_f32_16x16x32_bf16 v[48:51], v[168:171], v[176:179], v[48:51]
	v_mfma_f32_16x16x32_bf16 v[36:39], v[160:163], v[186:189], v[36:39]
	v_mfma_f32_16x16x32_bf16 v[32:35], v[168:171], v[186:189], v[32:35]
	v_mfma_f32_16x16x32_bf16 v[20:23], v[160:163], v[196:199], v[20:23]
	v_mfma_f32_16x16x32_bf16 v[16:19], v[168:171], v[196:199], v[16:19]
	v_mfma_f32_16x16x32_bf16 v[4:7], v[160:163], v[204:207], v[4:7]
	v_mfma_f32_16x16x32_bf16 v[0:3], v[168:171], v[204:207], v[0:3]
	s_barrier
	s_add_i32 s70, s70, 2
	s_add_u32 s36, s36, 0x100
	s_addc_u32 s37, s37, 0
	s_cmp_gt_u32 s70, 41
	s_mov_b64 s[96:97], s[44:45]
	s_cbranch_scc0 .LBB0_957
	s_setprio 0
	s_and_b64 vcc, exec, s[58:59]
	s_cbranch_vccz .LBB0_960
	s_barrier

; #define PG8_STAGE(bufoff, gbase, voff) do { _Pragma("unroll") for (int _i = 0; _i < 2; ++_i) \
;         __builtin_amdgcn_global_load_lds((const unsigned*)((const char*)(gbase) + (voff)[_i]), (PG8_LAS unsigned*)(lds + (bufoff) + ldsw + _i * 8192), 16, 0, 0); } while (0)
; #define PG8_LDA(dst, b, h) do { _Pragma("unroll") for (int m = 0; m < 4; ++m) _Pragma("unroll") for (int k = 0; k < 2; ++k) dst[m][k] = *(const PG8_LAS bf16x8*)(lds + PG8_SA(b, h) + aoff + m * 2048 + k * 1024); } while (0)
; #define PG8_LDB(dst, b, h) do { _Pragma("unroll") for (int n = 0; n < 2; ++n) _Pragma("unroll") for (int k = 0; k < 2; ++k) dst[n][k] = *(const PG8_LAS bf16x8*)(lds + PG8_SB(b, h) + boff + n * 2048 + k * 1024); } while (0)
; #define PG8_WAIT_V(n) asm volatile("s_waitcnt vmcnt(" #n ")" ::: "memory")
; #define PG8_WAIT_L(n) asm volatile("s_waitcnt lgkmcnt(" #n ")" ::: "memory")
; #define PG8_BAR __builtin_amdgcn_s_barrier()
; #define PG8_SCHED __builtin_amdgcn_sched_barrier(0)
; template <class Epi, class Sched, bool ALIGN_EPI = false, bool SP2 = false>
; __device__ __forceinline__ void gemm_phase(PG8_LAS unsigned char* lds, const Gemm g, const Sched& S, const Epi& E) {
;     ...
;         const bool has_next = S.next(ui + 1, nxt);
;         const char* nA = has_next ? (const char*)g.A + (size_t)nxt.pm * tstep : cA; const char* nB = has_next ? (const char*)g.Bt + (size_t)nxt.pn * tstep : cB;
;         for (int t = 0; t < nt; t += 2) {
;             const bool last = (t == nt - 2);
;             const char* a1 = cA + (size_t)(t + 1) * kstep;
;             const char* a2 = last ? nA : cA + (size_t)(t + 2) * kstep; const char* b2 = last ? nB : cB + (size_t)(t + 2) * kstep;
;             const char* a3 = a2 + kstep; const char* b3 = b2 + kstep;
;             if (last && has_next) S.a_ready(nxt);
;             if constexpr (SP2) {
;             PG8_LDB(B0, 0, 0); PG8_LDB(B1, 0, 1); PG8_SCHED; PG8_LDA(At, 0, 0); PG8_STAGE(PG8_SA(1, 1), a1 + hstep, voffA);
;             PG8_WAIT_V(8); PG8_WAIT_L(0); PG8_BAR; PG8_MMA(0, 0, At, B0); PG8_MMA(0, 1, At, B1); PG8_BAR; PG8_SCHED;
;             PG8_LDA(At, 0, 1); PG8_STAGE(PG8_SB(0, 0), b2, voffB); PG8_STAGE(PG8_SB(0, 1), b2 + hstep, voffB); PG8_STAGE(PG8_SA(0, 0), a2, voffA);
;             PG8_WAIT_V(8); PG8_WAIT_L(0); PG8_BAR; PG8_MMA(1, 0, At, B0); PG8_MMA(1, 1, At, B1); PG8_BAR; PG8_SCHED;
.Lsp_5:
.LBB0_995:
	s_add_u32 s42, s96, 0x100
	s_addc_u32 s43, s97, 0
	s_add_i32 s8, 0, 0x10000
	s_cmp_eq_u32 s84, 40
	s_cselect_b32 s65, s67, s43
	s_cselect_b32 s64, s66, s42
	s_cselect_b32 s47, s73, s37
	s_cselect_b32 s46, s72, s36
	s_add_i32 s85, 0, 0x14000
	v_add_u32_e32 v142, s8, v201
	v_add_u32_e32 v168, s85, v201
	ds_read_b128 v[130:133], v142
	ds_read_b128 v[134:137], v142 offset:1024
	ds_read_b128 v[138:141], v142 offset:2048
	ds_read_b128 v[142:145], v142 offset:3072
	ds_read_b128 v[156:159], v168
	ds_read_b128 v[160:163], v168 offset:1024
	ds_read_b128 v[164:167], v168 offset:2048
	ds_read_b128 v[168:171], v168 offset:3072
	v_lshl_add_u64 v[208:209], s[96:97], 0, v[152:153]
	s_add_i32 m0, s15, 0xc000
	ds_read_b128 v[172:175], v203
	ds_read_b128 v[176:179], v203 offset:1024
	ds_read_b128 v[180:183], v203 offset:2048
	ds_read_b128 v[184:187], v203 offset:3072
	ds_read_b128 v[188:191], v203 offset:4096
	ds_read_b128 v[192:195], v203 offset:5120
	ds_read_b128 v[196:199], v203 offset:6144
	ds_read_b128 v[204:207], v203 offset:7168
	global_load_lds_dwordx4 v[208:209], off
	v_lshl_add_u64 v[208:209], s[96:97], 0, v[154:155]
	s_add_i32 m0, s15, 0xe000
	s_nop 0
	global_load_lds_dwordx4 v[208:209], off
	s_waitcnt vmcnt(8)
	s_waitcnt lgkmcnt(0)
	s_barrier
	v_mfma_f32_16x16x32_bf16 v[124:127], v[130:133], v[172:175], v[124:127]
	v_mfma_f32_16x16x32_bf16 v[120:123], v[138:141], v[172:175], v[120:123]
	v_mfma_f32_16x16x32_bf16 v[108:111], v[130:133], v[180:183], v[108:111]
	v_mfma_f32_16x16x32_bf16 v[104:107], v[138:141], v[180:183], v[104:107]
	v_mfma_f32_16x16x32_bf16 v[92:95], v[130:133], v[188:191], v[92:95]
	v_mfma_f32_16x16x32_bf16 v[88:91], v[138:141], v[188:191], v[88:91]
	v_mfma_f32_16x16x32_bf16 v[76:79], v[130:133], v[196:199], v[76:79]
	v_mfma_f32_16x16x32_bf16 v[72:75], v[138:141], v[196:199], v[72:75]
	v_mfma_f32_16x16x32_bf16 v[124:127], v[134:137], v[176:179], v[124:127]
	v_mfma_f32_16x16x32_bf16 v[120:123], v[142:145], v[176:179], v[120:123]
	v_mfma_f32_16x16x32_bf16 v[108:111], v[134:137], v[184:187], v[108:111]
	v_mfma_f32_16x16x32_bf16 v[104:107], v[142:145], v[184:187], v[104:107]
	v_mfma_f32_16x16x32_bf16 v[92:95], v[134:137], v[192:195], v[92:95]
	v_mfma_f32_16x16x32_bf16 v[88:91], v[142:145], v[192:195], v[88:91]
	v_mfma_f32_16x16x32_bf16 v[76:79], v[134:137], v[204:207], v[76:79]
	v_mfma_f32_16x16x32_bf16 v[72:75], v[142:145], v[204:207], v[72:75]
	v_mfma_f32_16x16x32_bf16 v[116:119], v[156:159], v[172:175], v[116:119]
	v_mfma_f32_16x16x32_bf16 v[112:115], v[164:167], v[172:175], v[112:115]
	v_mfma_f32_16x16x32_bf16 v[100:103], v[156:159], v[180:183], v[100:103]
	v_mfma_f32_16x16x32_bf16 v[96:99], v[164:167], v[180:183], v[96:99]
	v_mfma_f32_16x16x32_bf16 v[84:87], v[156:159], v[188:191], v[84:87]
	v_mfma_f32_16x16x32_bf16 v[80:83], v[164:167], v[188:191], v[80:83]
	v_mfma_f32_16x16x32_bf16 v[68:71], v[156:159], v[196:199], v[68:71]
	v_mfma_f32_16x16x32_bf16 v[64:67], v[164:167], v[196:199], v[64:67]
	v_mfma_f32_16x16x32_bf16 v[116:119], v[160:163], v[176:179], v[116:119]
	v_mfma_f32_16x16x32_bf16 v[112:115], v[168:171], v[176:179], v[112:115]
	v_mfma_f32_16x16x32_bf16 v[100:103], v[160:163], v[184:187], v[100:103]
	v_mfma_f32_16x16x32_bf16 v[96:99], v[168:171], v[184:187], v[96:99]
	v_mfma_f32_16x16x32_bf16 v[84:87], v[160:163], v[192:195], v[84:87]
	v_mfma_f32_16x16x32_bf16 v[80:83], v[168:171], v[192:195], v[80:83]
	v_mfma_f32_16x16x32_bf16 v[68:71], v[160:163], v[204:207], v[68:71]
	v_mfma_f32_16x16x32_bf16 v[64:67], v[168:171], v[204:207], v[64:67]
	s_barrier
	s_add_i32 s8, s8, s14
	v_lshl_add_u64 v[208:209], s[46:47], 0, v[128:129]
	s_mov_b32 m0, s8
	ds_read_b128 v[172:175], v203 offset:16384
	ds_read_b128 v[176:179], v203 offset:17408
	ds_read_b128 v[180:183], v203 offset:18432
	ds_read_b128 v[184:187], v203 offset:19456
	ds_read_b128 v[188:191], v203 offset:20480
	ds_read_b128 v[192:195], v203 offset:21504
	ds_read_b128 v[196:199], v203 offset:22528
	ds_read_b128 v[204:207], v203 offset:23552
	global_load_lds_dwordx4 v[208:209], off
	s_add_i32 m0, s8, 0x2000
	s_add_u32 s96, s46, 0xb0000
	v_lshl_add_u64 v[210:211], s[46:47], 0, v[146:147]
	s_addc_u32 s97, s47, 0
	s_add_i32 s8, s85, s14
	global_load_lds_dwordx4 v[210:211], off
	v_lshl_add_u64 v[214:215], s[96:97], 0, v[128:129]
	s_mov_b32 m0, s8
	v_lshl_add_u64 v[222:223], s[64:65], 0, v[148:149]
	global_load_lds_dwordx4 v[214:215], off
	v_lshl_add_u64 v[214:215], s[96:97], 0, v[146:147]
	s_add_i32 m0, s8, 0x2000
	s_nop 0
	global_load_lds_dwordx4 v[214:215], off
	v_lshl_add_u64 v[214:215], s[64:65], 0, v[150:151]
	s_mov_b32 m0, s15
	s_nop 0
	global_load_lds_dwordx4 v[214:215], off
	s_mov_b32 m0, s18
	s_nop 0
	global_load_lds_dwordx4 v[222:223], off
	s_waitcnt vmcnt(8)
	s_waitcnt lgkmcnt(0)
	s_barrier
; #define PG8_STAGE(bufoff, gbase, voff) do { _Pragma("unroll") for (int _i = 0; _i < 2; ++_i) \
;         __builtin_amdgcn_global_load_lds((const unsigned*)((const char*)(gbase) + (voff)[_i]), (PG8_LAS unsigned*)(lds + (bufoff) + ldsw + _i * 8192), 16, 0, 0); } while (0)
; #define PG8_LDA(dst, b, h) do { _Pragma("unroll") for (int m = 0; m < 4; ++m) _Pragma("unroll") for (int k = 0; k < 2; ++k) dst[m][k] = *(const PG8_LAS bf16x8*)(lds + PG8_SA(b, h) + aoff + m * 2048 + k * 1024); } while (0)
; #define PG8_LDB(dst, b, h) do { _Pragma("unroll") for (int n = 0; n < 2; ++n) _Pragma("unroll") for (int k = 0; k < 2; ++k) dst[n][k] = *(const PG8_LAS bf16x8*)(lds + PG8_SB(b, h) + boff + n * 2048 + k * 1024); } while (0)
; #define PG8_MMA(ai, bj, At, Bt) do { __builtin_amdgcn_s_setprio(1); _Pragma("unroll") for (int m = 0; m < 4; ++m) _Pragma("unroll") for (int n = 0; n < 2; ++n) _Pragma("unroll") for (int k = 0; k < 2; ++k) \
;         acc[ai][bj][m][n] = __builtin_amdgcn_mfma_f32_16x16x32_bf16(Bt[n][k], At[m][k], acc[ai][bj][m][n], 0, 0, 0); __builtin_amdgcn_s_setprio(0); } while (0)
; #define PG8_WAIT_V(n) asm volatile("s_waitcnt vmcnt(" #n ")" ::: "memory")
; #define PG8_WAIT_L(n) asm volatile("s_waitcnt lgkmcnt(" #n ")" ::: "memory")
; #define PG8_BAR __builtin_amdgcn_s_barrier()
; #define PG8_SCHED __builtin_amdgcn_sched_barrier(0)
; template <class Epi, class Sched, bool ALIGN_EPI = false, bool SP2 = false>
; __device__ __forceinline__ void gemm_phase(PG8_LAS unsigned char* lds, const Gemm g, const Sched& S, const Epi& E) {
;     ...
;             PG8_LDA(At, 0, 1); PG8_STAGE(PG8_SB(0, 0), b2, voffB); PG8_STAGE(PG8_SB(0, 1), b2 + hstep, voffB); PG8_STAGE(PG8_SA(0, 0), a2, voffA);
;             PG8_WAIT_V(8); PG8_WAIT_L(0); PG8_BAR; PG8_MMA(1, 0, At, B0); PG8_MMA(1, 1, At, B1); PG8_BAR; PG8_SCHED;
;             PG8_LDB(B0, 1, 0); PG8_LDB(B1, 1, 1); PG8_SCHED; PG8_LDA(At, 1, 0); PG8_STAGE(PG8_SA(0, 1), a2 + hstep, voffA);
;             PG8_WAIT_V(8); PG8_WAIT_L(0); PG8_BAR; PG8_MMA(0, 0, At, B0); PG8_MMA(0, 1, At, B1); PG8_BAR; PG8_SCHED;
	v_mfma_f32_16x16x32_bf16 v[60:63], v[130:133], v[172:175], v[60:63]
	v_mfma_f32_16x16x32_bf16 v[56:59], v[138:141], v[172:175], v[56:59]
	v_mfma_f32_16x16x32_bf16 v[44:47], v[130:133], v[180:183], v[44:47]
	v_mfma_f32_16x16x32_bf16 v[40:43], v[138:141], v[180:183], v[40:43]
	v_mfma_f32_16x16x32_bf16 v[28:31], v[130:133], v[188:191], v[28:31]
	v_mfma_f32_16x16x32_bf16 v[24:27], v[138:141], v[188:191], v[24:27]
	v_mfma_f32_16x16x32_bf16 v[12:15], v[130:133], v[196:199], v[12:15]
	v_mfma_f32_16x16x32_bf16 v[8:11], v[138:141], v[196:199], v[8:11]
	v_mfma_f32_16x16x32_bf16 v[60:63], v[134:137], v[176:179], v[60:63]
	v_mfma_f32_16x16x32_bf16 v[56:59], v[142:145], v[176:179], v[56:59]
	v_mfma_f32_16x16x32_bf16 v[44:47], v[134:137], v[184:187], v[44:47]
	v_mfma_f32_16x16x32_bf16 v[40:43], v[142:145], v[184:187], v[40:43]
	v_mfma_f32_16x16x32_bf16 v[28:31], v[134:137], v[192:195], v[28:31]
	v_mfma_f32_16x16x32_bf16 v[24:27], v[142:145], v[192:195], v[24:27]
	v_mfma_f32_16x16x32_bf16 v[12:15], v[134:137], v[204:207], v[12:15]
	v_mfma_f32_16x16x32_bf16 v[8:11], v[142:145], v[204:207], v[8:11]
	v_mfma_f32_16x16x32_bf16 v[52:55], v[156:159], v[172:175], v[52:55]
	v_mfma_f32_16x16x32_bf16 v[48:51], v[164:167], v[172:175], v[48:51]
	v_mfma_f32_16x16x32_bf16 v[36:39], v[156:159], v[180:183], v[36:39]
	v_mfma_f32_16x16x32_bf16 v[32:35], v[164:167], v[180:183], v[32:35]
	v_mfma_f32_16x16x32_bf16 v[20:23], v[156:159], v[188:191], v[20:23]
	v_mfma_f32_16x16x32_bf16 v[16:19], v[164:167], v[188:191], v[16:19]
	v_mfma_f32_16x16x32_bf16 v[4:7], v[156:159], v[196:199], v[4:7]
	v_mfma_f32_16x16x32_bf16 v[0:3], v[164:167], v[196:199], v[0:3]
	v_mfma_f32_16x16x32_bf16 v[52:55], v[160:163], v[176:179], v[52:55]
	v_mfma_f32_16x16x32_bf16 v[48:51], v[168:171], v[176:179], v[48:51]
	v_mfma_f32_16x16x32_bf16 v[36:39], v[160:163], v[184:187], v[36:39]
	v_mfma_f32_16x16x32_bf16 v[32:35], v[168:171], v[184:187], v[32:35]
	v_mfma_f32_16x16x32_bf16 v[20:23], v[160:163], v[192:195], v[20:23]
	v_mfma_f32_16x16x32_bf16 v[16:19], v[168:171], v[192:195], v[16:19]
	v_mfma_f32_16x16x32_bf16 v[4:7], v[160:163], v[204:207], v[4:7]
	v_mfma_f32_16x16x32_bf16 v[0:3], v[168:171], v[204:207], v[0:3]
	s_barrier
	s_add_i32 s8, 0, 0x18000
	s_add_i32 s85, 0, 0x1c000
	v_add_u32_e32 v142, s8, v201
	v_add_u32_e32 v168, s85, v201
	ds_read_b128 v[130:133], v142
	ds_read_b128 v[134:137], v142 offset:1024
	ds_read_b128 v[138:141], v142 offset:2048
	ds_read_b128 v[142:145], v142 offset:3072
	ds_read_b128 v[156:159], v168
	ds_read_b128 v[160:163], v168 offset:1024
	ds_read_b128 v[164:167], v168 offset:2048
	ds_read_b128 v[168:171], v168 offset:3072
	s_add_u32 s64, s64, 0xb0000
	s_addc_u32 s65, s65, 0
	s_mov_b32 m0, s19
	v_lshl_add_u64 v[228:229], s[64:65], 0, v[150:151]
	ds_read_b128 v[172:175], v203 offset:32768
	ds_read_b128 v[176:179], v203 offset:33792
	ds_read_b128 v[180:183], v203 offset:34816
	ds_read_b128 v[184:187], v203 offset:35840
	ds_read_b128 v[188:191], v203 offset:36864
	ds_read_b128 v[192:195], v203 offset:37888
	ds_read_b128 v[196:199], v203 offset:38912
	ds_read_b128 v[204:207], v203 offset:39936
	global_load_lds_dwordx4 v[228:229], off
	v_lshl_add_u64 v[228:229], s[64:65], 0, v[148:149]
	s_mov_b32 m0, s20
	s_nop 0
	global_load_lds_dwordx4 v[228:229], off
	s_waitcnt vmcnt(8)
	s_waitcnt lgkmcnt(0)
	s_barrier
	v_mfma_f32_16x16x32_bf16 v[124:127], v[130:133], v[172:175], v[124:127]
	v_mfma_f32_16x16x32_bf16 v[120:123], v[138:141], v[172:175], v[120:123]
	v_mfma_f32_16x16x32_bf16 v[108:111], v[130:133], v[180:183], v[108:111]
	v_mfma_f32_16x16x32_bf16 v[104:107], v[138:141], v[180:183], v[104:107]
	v_mfma_f32_16x16x32_bf16 v[92:95], v[130:133], v[188:191], v[92:95]
	v_mfma_f32_16x16x32_bf16 v[88:91], v[138:141], v[188:191], v[88:91]
	v_mfma_f32_16x16x32_bf16 v[76:79], v[130:133], v[196:199], v[76:79]
	v_mfma_f32_16x16x32_bf16 v[72:75], v[138:141], v[196:199], v[72:75]
	v_mfma_f32_16x16x32_bf16 v[124:127], v[134:137], v[176:179], v[124:127]
	v_mfma_f32_16x16x32_bf16 v[120:123], v[142:145], v[176:179], v[120:123]
	v_mfma_f32_16x16x32_bf16 v[108:111], v[134:137], v[184:187], v[108:111]
	v_mfma_f32_16x16x32_bf16 v[104:107], v[142:145], v[184:187], v[104:107]
	v_mfma_f32_16x16x32_bf16 v[92:95], v[134:137], v[192:195], v[92:95]
	v_mfma_f32_16x16x32_bf16 v[88:91], v[142:145], v[192:195], v[88:91]
	v_mfma_f32_16x16x32_bf16 v[76:79], v[134:137], v[204:207], v[76:79]
	v_mfma_f32_16x16x32_bf16 v[72:75], v[142:145], v[204:207], v[72:75]
	v_mfma_f32_16x16x32_bf16 v[116:119], v[156:159], v[172:175], v[116:119]
	v_mfma_f32_16x16x32_bf16 v[112:115], v[164:167], v[172:175], v[112:115]
	v_mfma_f32_16x16x32_bf16 v[100:103], v[156:159], v[180:183], v[100:103]
	v_mfma_f32_16x16x32_bf16 v[96:99], v[164:167], v[180:183], v[96:99]
	v_mfma_f32_16x16x32_bf16 v[84:87], v[156:159], v[188:191], v[84:87]
	v_mfma_f32_16x16x32_bf16 v[80:83], v[164:167], v[188:191], v[80:83]
	v_mfma_f32_16x16x32_bf16 v[68:71], v[156:159], v[196:199], v[68:71]
	v_mfma_f32_16x16x32_bf16 v[64:67], v[164:167], v[196:199], v[64:67]
	v_mfma_f32_16x16x32_bf16 v[116:119], v[160:163], v[176:179], v[116:119]
	v_mfma_f32_16x16x32_bf16 v[112:115], v[168:171], v[176:179], v[112:115]
	v_mfma_f32_16x16x32_bf16 v[100:103], v[160:163], v[184:187], v[100:103]
	v_mfma_f32_16x16x32_bf16 v[96:99], v[168:171], v[184:187], v[96:99]
	v_mfma_f32_16x16x32_bf16 v[84:87], v[160:163], v[192:195], v[84:87]
	v_mfma_f32_16x16x32_bf16 v[80:83], v[168:171], v[192:195], v[80:83]
	v_mfma_f32_16x16x32_bf16 v[68:71], v[160:163], v[204:207], v[68:71]
	v_mfma_f32_16x16x32_bf16 v[64:67], v[168:171], v[204:207], v[64:67]
	s_barrier
; #define PG8_STAGE(bufoff, gbase, voff) do { _Pragma("unroll") for (int _i = 0; _i < 2; ++_i) \
;         __builtin_amdgcn_global_load_lds((const unsigned*)((const char*)(gbase) + (voff)[_i]), (PG8_LAS unsigned*)(lds + (bufoff) + ldsw + _i * 8192), 16, 0, 0); } while (0)
; #define PG8_LDA(dst, b, h) do { _Pragma("unroll") for (int m = 0; m < 4; ++m) _Pragma("unroll") for (int k = 0; k < 2; ++k) dst[m][k] = *(const PG8_LAS bf16x8*)(lds + PG8_SA(b, h) + aoff + m * 2048 + k * 1024); } while (0)
; #define PG8_MMA(ai, bj, At, Bt) do { __builtin_amdgcn_s_setprio(1); _Pragma("unroll") for (int m = 0; m < 4; ++m) _Pragma("unroll") for (int n = 0; n < 2; ++n) _Pragma("unroll") for (int k = 0; k < 2; ++k) \
;         acc[ai][bj][m][n] = __builtin_amdgcn_mfma_f32_16x16x32_bf16(Bt[n][k], At[m][k], acc[ai][bj][m][n], 0, 0, 0); __builtin_amdgcn_s_setprio(0); } while (0)
; #define PG8_WAIT_V(n) asm volatile("s_waitcnt vmcnt(" #n ")" ::: "memory")
; #define PG8_WAIT_L(n) asm volatile("s_waitcnt lgkmcnt(" #n ")" ::: "memory")
; #define PG8_BAR __builtin_amdgcn_s_barrier()
; #define PG8_SCHED __builtin_amdgcn_sched_barrier(0)
; template <class Epi, class Sched, bool ALIGN_EPI = false, bool SP2 = false>
; __device__ __forceinline__ void gemm_phase(PG8_LAS unsigned char* lds, const Gemm g, const Sched& S, const Epi& E) {
;     ...
;         for (int t = 0; t < nt; t += 2) {
;             const bool last = (t == nt - 2);
;             const char* a1 = cA + (size_t)(t + 1) * kstep;
;             const char* a2 = last ? nA : cA + (size_t)(t + 2) * kstep; const char* b2 = last ? nB : cB + (size_t)(t + 2) * kstep;
;             const char* a3 = a2 + kstep; const char* b3 = b2 + kstep;
;     ...
;             PG8_LDA(At, 1, 1); PG8_STAGE(PG8_SB(1, 0), b3, voffB); PG8_STAGE(PG8_SB(1, 1), b3 + hstep, voffB); PG8_STAGE(PG8_SA(1, 0), a3, voffA);
;             PG8_WAIT_V(8); PG8_WAIT_L(0); PG8_BAR; PG8_MMA(1, 0, At, B0); PG8_MMA(1, 1, At, B1); PG8_BAR; PG8_SCHED;
	s_add_i32 s8, s8, s14
	v_lshl_add_u64 v[208:209], v[208:209], 0, s[90:91]
	s_mov_b32 m0, s8
	ds_read_b128 v[172:175], v203 offset:49152
	ds_read_b128 v[176:179], v203 offset:50176
	ds_read_b128 v[180:183], v203 offset:51200
	ds_read_b128 v[184:187], v203 offset:52224
	ds_read_b128 v[188:191], v203 offset:53248
	ds_read_b128 v[192:195], v203 offset:54272
	ds_read_b128 v[196:199], v203 offset:55296
	ds_read_b128 v[204:207], v203 offset:56320
	global_load_lds_dwordx4 v[208:209], off
	s_add_i32 m0, s8, 0x2000
	s_add_u32 s46, s46, 0xb0080
	v_lshl_add_u64 v[208:209], v[210:211], 0, s[90:91]
	s_addc_u32 s47, s47, 0
	s_add_i32 s8, s85, s14
	global_load_lds_dwordx4 v[208:209], off
	v_lshl_add_u64 v[208:209], s[46:47], 0, v[128:129]
	s_mov_b32 m0, s8
	s_nop 0
	global_load_lds_dwordx4 v[208:209], off
	v_lshl_add_u64 v[208:209], s[46:47], 0, v[146:147]
	s_add_i32 m0, s8, 0x2000
	s_nop 0
	global_load_lds_dwordx4 v[208:209], off
	v_lshl_add_u64 v[208:209], v[214:215], 0, s[90:91]
	s_mov_b32 m0, s29
	s_nop 0
	global_load_lds_dwordx4 v[208:209], off
	v_lshl_add_u64 v[208:209], v[222:223], 0, s[90:91]
	s_mov_b32 m0, s30
	s_nop 0
	global_load_lds_dwordx4 v[208:209], off
	s_waitcnt vmcnt(8)
	s_waitcnt lgkmcnt(0)
	s_barrier
	v_mfma_f32_16x16x32_bf16 v[60:63], v[130:133], v[172:175], v[60:63]
	v_mfma_f32_16x16x32_bf16 v[56:59], v[138:141], v[172:175], v[56:59]
	v_mfma_f32_16x16x32_bf16 v[44:47], v[130:133], v[180:183], v[44:47]
	v_mfma_f32_16x16x32_bf16 v[40:43], v[138:141], v[180:183], v[40:43]
	v_mfma_f32_16x16x32_bf16 v[28:31], v[130:133], v[188:191], v[28:31]
	v_mfma_f32_16x16x32_bf16 v[24:27], v[138:141], v[188:191], v[24:27]
	v_mfma_f32_16x16x32_bf16 v[12:15], v[130:133], v[196:199], v[12:15]
	v_mfma_f32_16x16x32_bf16 v[8:11], v[138:141], v[196:199], v[8:11]
	v_mfma_f32_16x16x32_bf16 v[60:63], v[134:137], v[176:179], v[60:63]
	v_mfma_f32_16x16x32_bf16 v[56:59], v[142:145], v[176:179], v[56:59]
	v_mfma_f32_16x16x32_bf16 v[44:47], v[134:137], v[184:187], v[44:47]
	v_mfma_f32_16x16x32_bf16 v[40:43], v[142:145], v[184:187], v[40:43]
	v_mfma_f32_16x16x32_bf16 v[28:31], v[134:137], v[192:195], v[28:31]
	v_mfma_f32_16x16x32_bf16 v[24:27], v[142:145], v[192:195], v[24:27]
	v_mfma_f32_16x16x32_bf16 v[12:15], v[134:137], v[204:207], v[12:15]
	v_mfma_f32_16x16x32_bf16 v[8:11], v[142:145], v[204:207], v[8:11]
	v_mfma_f32_16x16x32_bf16 v[52:55], v[156:159], v[172:175], v[52:55]
	v_mfma_f32_16x16x32_bf16 v[48:51], v[164:167], v[172:175], v[48:51]
	v_mfma_f32_16x16x32_bf16 v[36:39], v[156:159], v[180:183], v[36:39]
	v_mfma_f32_16x16x32_bf16 v[32:35], v[164:167], v[180:183], v[32:35]
	v_mfma_f32_16x16x32_bf16 v[20:23], v[156:159], v[188:191], v[20:23]
	v_mfma_f32_16x16x32_bf16 v[16:19], v[164:167], v[188:191], v[16:19]
	v_mfma_f32_16x16x32_bf16 v[4:7], v[156:159], v[196:199], v[4:7]
	v_mfma_f32_16x16x32_bf16 v[0:3], v[164:167], v[196:199], v[0:3]
	v_mfma_f32_16x16x32_bf16 v[52:55], v[160:163], v[176:179], v[52:55]
	v_mfma_f32_16x16x32_bf16 v[48:51], v[168:171], v[176:179], v[48:51]
	v_mfma_f32_16x16x32_bf16 v[36:39], v[160:163], v[184:187], v[36:39]
	v_mfma_f32_16x16x32_bf16 v[32:35], v[168:171], v[184:187], v[32:35]
	v_mfma_f32_16x16x32_bf16 v[20:23], v[160:163], v[192:195], v[20:23]
	v_mfma_f32_16x16x32_bf16 v[16:19], v[168:171], v[192:195], v[16:19]
	v_mfma_f32_16x16x32_bf16 v[4:7], v[160:163], v[204:207], v[4:7]
	v_mfma_f32_16x16x32_bf16 v[0:3], v[168:171], v[204:207], v[0:3]
	s_barrier
	s_add_i32 s84, s84, 2
	s_add_u32 s36, s36, 0x100
	s_addc_u32 s37, s37, 0
	s_cmp_gt_u32 s84, 41
	s_mov_b64 s[96:97], s[42:43]
	s_cbranch_scc0 .LBB0_995
	s_setprio 0
	s_and_b64 vcc, exec, s[62:63]
	s_cbranch_vccz .LBB0_998
	s_barrier
